# FFN1 epilogue: hoist 8 rstd loads, drop per-group vmcnt(0); GMA/GMB epilogue waits vmcnt(0)->vmcnt(1) keeping stores in flight
# speedup vs baseline: 1.0091x; 1.0091x over previous
.LBB0_1182:
	s_lshl_b32 s0, s60, 8
	v_mov_b32_e32 v142, v147
	v_mov_b32_e32 v143, v146
	s_add_i32 s0, s0, s51
	s_and_b64 vcc, exec, s[2:3]
	v_add_u32_e32 v144, s0, v142
	s_lshl_b32 s0, s59, 8
	s_or_b32 s0, s0, s52
	v_lshl_add_u32 v142, v143, 3, s0
	v_ashrrev_i32_e32 v145, 31, v144
	v_lshlrev_b64 v[152:153], 13, v[144:145]
	v_ashrrev_i32_e32 v143, 31, v142
	v_lshl_add_u64 v[152:153], s[16:17], 0, v[152:153]
	v_lshlrev_b64 v[142:143], 1, v[142:143]
	v_lshl_add_u64 v[156:157], v[152:153], 0, v[142:143]
	global_load_dwordx4 v[152:155], v[156:157], off
	s_mov_b64 s[2:3], -1
	s_waitcnt vmcnt(0)
	v_lshlrev_b32_e32 v158, 16, v152
	v_and_b32_e32 v152, 0xffff0000, v152
	v_lshlrev_b32_e32 v159, 16, v153
	v_and_b32_e32 v153, 0xffff0000, v153
	v_lshlrev_b32_e32 v161, 16, v155
	v_and_b32_e32 v155, 0xffff0000, v155
	v_lshlrev_b32_e32 v160, 16, v154
	v_and_b32_e32 v154, 0xffff0000, v154
	v_fma_f32 v124, v124, v158, 0
	v_fma_f32 v125, v125, v152, 0
	v_fma_f32 v126, v126, v159, 0
	v_fma_f32 v127, v127, v153, 0
	v_fma_f32 v123, v123, v155, 0
	v_fma_f32 v152, v120, v160, 0
	v_fma_f32 v153, v121, v154, 0
	v_fma_f32 v154, v122, v161, 0
	v_cvt_pk_bf16_f32 v120, v124, v125
	v_cvt_pk_bf16_f32 v121, v126, v127
	v_cvt_pk_bf16_f32 v122, v152, v153
	v_cvt_pk_bf16_f32 v123, v154, v123
	global_load_dwordx4 v[124:127], v[156:157], off offset:256
	v_add_u32_e32 v152, 16, v144
	v_lshlrev_b64 v[154:155], 12, v[144:145]
	v_ashrrev_i32_e32 v153, 31, v152
	v_lshl_add_u64 v[154:155], s[14:15], 0, v[154:155]
	v_lshlrev_b64 v[156:157], 13, v[152:153]
	v_lshl_add_u64 v[154:155], v[154:155], 0, v[142:143]
	v_lshl_add_u64 v[156:157], s[16:17], 0, v[156:157]
	global_store_dwordx4 v[154:155], v[120:123], off
	v_lshl_add_u64 v[156:157], v[156:157], 0, v[142:143]
	s_waitcnt vmcnt(1)
	v_lshlrev_b32_e32 v120, 16, v124
	v_and_b32_e32 v121, 0xffff0000, v124
	v_lshlrev_b32_e32 v122, 16, v125
	v_and_b32_e32 v123, 0xffff0000, v125
	v_lshlrev_b32_e32 v124, 16, v126
	v_and_b32_e32 v125, 0xffff0000, v126
	v_lshlrev_b32_e32 v126, 16, v127
	v_and_b32_e32 v127, 0xffff0000, v127
	v_fma_f32 v116, v116, v120, 0
	v_fma_f32 v117, v117, v121, 0
	v_fma_f32 v118, v118, v122, 0
	v_fma_f32 v119, v119, v123, 0
	v_fma_f32 v115, v115, v127, 0
	v_fma_f32 v120, v112, v124, 0
	v_fma_f32 v121, v113, v125, 0
	v_fma_f32 v122, v114, v126, 0
	v_cvt_pk_bf16_f32 v112, v116, v117
	v_cvt_pk_bf16_f32 v113, v118, v119
	v_cvt_pk_bf16_f32 v114, v120, v121
	v_cvt_pk_bf16_f32 v115, v122, v115
	global_load_dwordx4 v[116:119], v[156:157], off
	s_nop 0
	global_store_dwordx4 v[154:155], v[112:115], off offset:256
	s_waitcnt vmcnt(1)
	s_nop 0
	v_lshlrev_b32_e32 v112, 16, v116
	v_and_b32_e32 v113, 0xffff0000, v116
	v_lshlrev_b32_e32 v114, 16, v117
	v_and_b32_e32 v115, 0xffff0000, v117
	v_lshlrev_b32_e32 v116, 16, v118
	v_and_b32_e32 v117, 0xffff0000, v118
	v_lshlrev_b32_e32 v118, 16, v119
	v_and_b32_e32 v119, 0xffff0000, v119
	v_fma_f32 v108, v108, v112, 0
	v_fma_f32 v109, v109, v113, 0
	v_fma_f32 v110, v110, v114, 0
	v_fma_f32 v111, v111, v115, 0
	v_fma_f32 v107, v107, v119, 0
	v_fma_f32 v112, v104, v116, 0
	v_fma_f32 v113, v105, v117, 0
	v_fma_f32 v114, v106, v118, 0
	v_cvt_pk_bf16_f32 v104, v108, v109
	v_cvt_pk_bf16_f32 v105, v110, v111
	v_cvt_pk_bf16_f32 v106, v112, v113
	v_cvt_pk_bf16_f32 v107, v114, v107
	global_load_dwordx4 v[108:111], v[156:157], off offset:256
	v_add_u32_e32 v112, 32, v144
	v_lshlrev_b64 v[114:115], 12, v[152:153]
	v_ashrrev_i32_e32 v113, 31, v112
	v_lshl_add_u64 v[114:115], s[14:15], 0, v[114:115]
	v_lshlrev_b64 v[116:117], 13, v[112:113]
	v_lshl_add_u64 v[114:115], v[114:115], 0, v[142:143]
	v_lshl_add_u64 v[116:117], s[16:17], 0, v[116:117]
	global_store_dwordx4 v[114:115], v[104:107], off
	v_lshl_add_u64 v[116:117], v[116:117], 0, v[142:143]
	s_waitcnt vmcnt(1)
	v_lshlrev_b32_e32 v104, 16, v108
	v_and_b32_e32 v105, 0xffff0000, v108
	v_lshlrev_b32_e32 v106, 16, v109
	v_and_b32_e32 v107, 0xffff0000, v109
	v_lshlrev_b32_e32 v108, 16, v110
	v_and_b32_e32 v109, 0xffff0000, v110
	v_lshlrev_b32_e32 v110, 16, v111
	v_and_b32_e32 v111, 0xffff0000, v111
	v_fma_f32 v100, v100, v104, 0
	v_fma_f32 v101, v101, v105, 0
	v_fma_f32 v102, v102, v106, 0
	v_fma_f32 v103, v103, v107, 0
	v_fma_f32 v99, v99, v111, 0
	v_fma_f32 v104, v96, v108, 0
	v_fma_f32 v105, v97, v109, 0
	v_fma_f32 v106, v98, v110, 0
	v_cvt_pk_bf16_f32 v96, v100, v101
	v_cvt_pk_bf16_f32 v97, v102, v103
	v_cvt_pk_bf16_f32 v98, v104, v105
	v_cvt_pk_bf16_f32 v99, v106, v99
	global_load_dwordx4 v[100:103], v[116:117], off
	s_nop 0
	global_store_dwordx4 v[114:115], v[96:99], off offset:256
	s_waitcnt vmcnt(1)
	s_nop 0
	v_lshlrev_b32_e32 v96, 16, v100
	v_and_b32_e32 v97, 0xffff0000, v100
	v_lshlrev_b32_e32 v98, 16, v101
	v_and_b32_e32 v99, 0xffff0000, v101
	v_lshlrev_b32_e32 v100, 16, v102
	v_and_b32_e32 v101, 0xffff0000, v102
	v_lshlrev_b32_e32 v102, 16, v103
	v_and_b32_e32 v103, 0xffff0000, v103
	v_fma_f32 v92, v92, v96, 0
	v_fma_f32 v93, v93, v97, 0
	v_fma_f32 v94, v94, v98, 0
	v_fma_f32 v95, v95, v99, 0
	v_fma_f32 v91, v91, v103, 0
	v_fma_f32 v96, v88, v100, 0
	v_fma_f32 v97, v89, v101, 0
	v_fma_f32 v98, v90, v102, 0
	v_cvt_pk_bf16_f32 v88, v92, v93
	v_cvt_pk_bf16_f32 v89, v94, v95
	v_cvt_pk_bf16_f32 v90, v96, v97
	v_cvt_pk_bf16_f32 v91, v98, v91
	global_load_dwordx4 v[92:95], v[116:117], off offset:256
	v_add_u32_e32 v96, 48, v144
	v_lshlrev_b64 v[98:99], 12, v[112:113]
	v_ashrrev_i32_e32 v97, 31, v96
	v_lshl_add_u64 v[98:99], s[14:15], 0, v[98:99]
	v_lshlrev_b64 v[100:101], 13, v[96:97]
	v_lshl_add_u64 v[98:99], v[98:99], 0, v[142:143]
	v_lshl_add_u64 v[100:101], s[16:17], 0, v[100:101]
	global_store_dwordx4 v[98:99], v[88:91], off
	v_lshl_add_u64 v[100:101], v[100:101], 0, v[142:143]
	s_waitcnt vmcnt(1)
	v_lshlrev_b32_e32 v88, 16, v92
	v_and_b32_e32 v89, 0xffff0000, v92
	v_lshlrev_b32_e32 v90, 16, v93
	v_and_b32_e32 v91, 0xffff0000, v93
	v_lshlrev_b32_e32 v92, 16, v94
	v_and_b32_e32 v93, 0xffff0000, v94
	v_lshlrev_b32_e32 v94, 16, v95
	v_and_b32_e32 v95, 0xffff0000, v95
	v_fma_f32 v84, v84, v88, 0
	v_fma_f32 v85, v85, v89, 0
	v_fma_f32 v86, v86, v90, 0
	v_fma_f32 v87, v87, v91, 0
	v_fma_f32 v83, v83, v95, 0
	v_fma_f32 v88, v80, v92, 0
	v_fma_f32 v89, v81, v93, 0
	v_fma_f32 v90, v82, v94, 0
	v_cvt_pk_bf16_f32 v80, v84, v85
	v_cvt_pk_bf16_f32 v81, v86, v87
	v_cvt_pk_bf16_f32 v82, v88, v89
	v_cvt_pk_bf16_f32 v83, v90, v83
	global_load_dwordx4 v[84:87], v[100:101], off
	s_nop 0
	global_store_dwordx4 v[98:99], v[80:83], off offset:256
	s_waitcnt vmcnt(1)
	s_nop 0
	v_lshlrev_b32_e32 v80, 16, v84
	v_and_b32_e32 v81, 0xffff0000, v84
	v_lshlrev_b32_e32 v82, 16, v85
	v_and_b32_e32 v83, 0xffff0000, v85
	v_lshlrev_b32_e32 v84, 16, v86
	v_and_b32_e32 v85, 0xffff0000, v86
	v_lshlrev_b32_e32 v86, 16, v87
	v_and_b32_e32 v87, 0xffff0000, v87
	v_fma_f32 v76, v76, v80, 0
	v_fma_f32 v77, v77, v81, 0
	v_fma_f32 v78, v78, v82, 0
	v_fma_f32 v79, v79, v83, 0
	v_fma_f32 v75, v75, v87, 0
	v_fma_f32 v80, v72, v84, 0
	v_fma_f32 v81, v73, v85, 0
	v_fma_f32 v82, v74, v86, 0
	v_cvt_pk_bf16_f32 v72, v76, v77
	v_cvt_pk_bf16_f32 v73, v78, v79
	v_cvt_pk_bf16_f32 v74, v80, v81
	v_cvt_pk_bf16_f32 v75, v82, v75
	global_load_dwordx4 v[76:79], v[100:101], off offset:256
	v_add_u32_e32 v80, 0x80, v144
	v_lshlrev_b64 v[82:83], 12, v[96:97]
	v_ashrrev_i32_e32 v81, 31, v80
	v_lshl_add_u64 v[82:83], s[14:15], 0, v[82:83]
	v_lshlrev_b64 v[84:85], 13, v[80:81]
	v_lshl_add_u64 v[82:83], v[82:83], 0, v[142:143]
	v_lshl_add_u64 v[84:85], s[16:17], 0, v[84:85]
	global_store_dwordx4 v[82:83], v[72:75], off
	v_lshl_add_u64 v[84:85], v[84:85], 0, v[142:143]
	s_waitcnt vmcnt(1)
	v_lshlrev_b32_e32 v72, 16, v76
	v_and_b32_e32 v73, 0xffff0000, v76
	v_lshlrev_b32_e32 v74, 16, v77
	v_and_b32_e32 v75, 0xffff0000, v77
	v_lshlrev_b32_e32 v76, 16, v78
	v_and_b32_e32 v77, 0xffff0000, v78
	v_lshlrev_b32_e32 v78, 16, v79
	v_and_b32_e32 v79, 0xffff0000, v79
	v_fma_f32 v68, v68, v72, 0
	v_fma_f32 v69, v69, v73, 0
	v_fma_f32 v70, v70, v74, 0
	v_fma_f32 v71, v71, v75, 0
	v_fma_f32 v67, v67, v79, 0
	v_fma_f32 v72, v64, v76, 0
	v_fma_f32 v73, v65, v77, 0
	v_fma_f32 v74, v66, v78, 0
	v_cvt_pk_bf16_f32 v64, v68, v69
	v_cvt_pk_bf16_f32 v65, v70, v71
	v_cvt_pk_bf16_f32 v66, v72, v73
	v_cvt_pk_bf16_f32 v67, v74, v67
	global_load_dwordx4 v[68:71], v[84:85], off
	s_nop 0
	global_store_dwordx4 v[82:83], v[64:67], off offset:256
	s_waitcnt vmcnt(1)
	s_nop 0
	v_lshlrev_b32_e32 v64, 16, v68
	v_and_b32_e32 v65, 0xffff0000, v68
	v_lshlrev_b32_e32 v66, 16, v69
	v_and_b32_e32 v67, 0xffff0000, v69
	v_lshlrev_b32_e32 v68, 16, v70
	v_and_b32_e32 v69, 0xffff0000, v70
	v_lshlrev_b32_e32 v70, 16, v71
	v_and_b32_e32 v71, 0xffff0000, v71
	v_fma_f32 v60, v60, v64, 0
	v_fma_f32 v61, v61, v65, 0
	v_fma_f32 v62, v62, v66, 0
	v_fma_f32 v63, v63, v67, 0
	v_fma_f32 v59, v59, v71, 0
	v_fma_f32 v64, v56, v68, 0
	v_fma_f32 v65, v57, v69, 0
	v_fma_f32 v66, v58, v70, 0
	v_cvt_pk_bf16_f32 v56, v60, v61
	v_cvt_pk_bf16_f32 v57, v62, v63
	v_cvt_pk_bf16_f32 v58, v64, v65
	v_cvt_pk_bf16_f32 v59, v66, v59
	global_load_dwordx4 v[60:63], v[84:85], off offset:256
	v_add_u32_e32 v64, 0x90, v144
	v_lshlrev_b64 v[66:67], 12, v[80:81]
	v_ashrrev_i32_e32 v65, 31, v64
	v_lshl_add_u64 v[66:67], s[14:15], 0, v[66:67]
	v_lshlrev_b64 v[68:69], 13, v[64:65]
	v_lshl_add_u64 v[66:67], v[66:67], 0, v[142:143]
	v_lshl_add_u64 v[68:69], s[16:17], 0, v[68:69]
	global_store_dwordx4 v[66:67], v[56:59], off
	v_lshl_add_u64 v[68:69], v[68:69], 0, v[142:143]
	s_waitcnt vmcnt(1)
	v_lshlrev_b32_e32 v56, 16, v60
	v_and_b32_e32 v57, 0xffff0000, v60
	v_lshlrev_b32_e32 v58, 16, v61
	v_and_b32_e32 v59, 0xffff0000, v61
	v_lshlrev_b32_e32 v60, 16, v62
	v_and_b32_e32 v61, 0xffff0000, v62
	v_lshlrev_b32_e32 v62, 16, v63
	v_and_b32_e32 v63, 0xffff0000, v63
	v_fma_f32 v52, v52, v56, 0
	v_fma_f32 v53, v53, v57, 0
	v_fma_f32 v54, v54, v58, 0
	v_fma_f32 v55, v55, v59, 0
	v_fma_f32 v51, v51, v63, 0
	v_fma_f32 v56, v48, v60, 0
	v_fma_f32 v57, v49, v61, 0
	v_fma_f32 v58, v50, v62, 0
	v_cvt_pk_bf16_f32 v48, v52, v53
	v_cvt_pk_bf16_f32 v49, v54, v55
	v_cvt_pk_bf16_f32 v50, v56, v57
	v_cvt_pk_bf16_f32 v51, v58, v51
	global_load_dwordx4 v[52:55], v[68:69], off
	s_nop 0
	global_store_dwordx4 v[66:67], v[48:51], off offset:256
	s_waitcnt vmcnt(1)
	s_nop 0
	v_lshlrev_b32_e32 v48, 16, v52
	v_and_b32_e32 v49, 0xffff0000, v52
	v_lshlrev_b32_e32 v50, 16, v53
	v_and_b32_e32 v51, 0xffff0000, v53
	v_lshlrev_b32_e32 v52, 16, v54
	v_and_b32_e32 v53, 0xffff0000, v54
	v_lshlrev_b32_e32 v54, 16, v55
	v_and_b32_e32 v55, 0xffff0000, v55
	v_fma_f32 v44, v44, v48, 0
	v_fma_f32 v45, v45, v49, 0
	v_fma_f32 v46, v46, v50, 0
	v_fma_f32 v47, v47, v51, 0
	v_fma_f32 v43, v43, v55, 0
	v_fma_f32 v48, v40, v52, 0
	v_fma_f32 v49, v41, v53, 0
	v_fma_f32 v50, v42, v54, 0
	v_cvt_pk_bf16_f32 v40, v44, v45
	v_cvt_pk_bf16_f32 v41, v46, v47
	v_cvt_pk_bf16_f32 v42, v48, v49
	v_cvt_pk_bf16_f32 v43, v50, v43
	global_load_dwordx4 v[44:47], v[68:69], off offset:256
	v_add_u32_e32 v48, 0xa0, v144
	v_lshlrev_b64 v[50:51], 12, v[64:65]
	v_ashrrev_i32_e32 v49, 31, v48
	v_lshl_add_u64 v[50:51], s[14:15], 0, v[50:51]
	v_lshlrev_b64 v[52:53], 13, v[48:49]
	v_lshl_add_u64 v[50:51], v[50:51], 0, v[142:143]
	v_lshl_add_u64 v[52:53], s[16:17], 0, v[52:53]
	global_store_dwordx4 v[50:51], v[40:43], off
	v_lshl_add_u64 v[52:53], v[52:53], 0, v[142:143]
	s_waitcnt vmcnt(1)
	v_lshlrev_b32_e32 v40, 16, v44
	v_and_b32_e32 v41, 0xffff0000, v44
	v_lshlrev_b32_e32 v42, 16, v45
	v_and_b32_e32 v43, 0xffff0000, v45
	v_lshlrev_b32_e32 v44, 16, v46
	v_and_b32_e32 v45, 0xffff0000, v46
	v_lshlrev_b32_e32 v46, 16, v47
	v_and_b32_e32 v47, 0xffff0000, v47
	v_fma_f32 v36, v36, v40, 0
	v_fma_f32 v37, v37, v41, 0
	v_fma_f32 v38, v38, v42, 0
	v_fma_f32 v39, v39, v43, 0
	v_fma_f32 v35, v35, v47, 0
	v_fma_f32 v40, v32, v44, 0
	v_fma_f32 v41, v33, v45, 0
	v_fma_f32 v42, v34, v46, 0
	v_cvt_pk_bf16_f32 v32, v36, v37
	v_cvt_pk_bf16_f32 v33, v38, v39
	v_cvt_pk_bf16_f32 v34, v40, v41
	v_cvt_pk_bf16_f32 v35, v42, v35
	global_load_dwordx4 v[36:39], v[52:53], off
	s_nop 0
	global_store_dwordx4 v[50:51], v[32:35], off offset:256
	s_waitcnt vmcnt(1)
	s_nop 0
	v_lshlrev_b32_e32 v32, 16, v36
	v_and_b32_e32 v33, 0xffff0000, v36
	v_lshlrev_b32_e32 v34, 16, v37
	v_and_b32_e32 v35, 0xffff0000, v37
	v_lshlrev_b32_e32 v36, 16, v38
	v_and_b32_e32 v37, 0xffff0000, v38
	v_lshlrev_b32_e32 v38, 16, v39
	v_and_b32_e32 v39, 0xffff0000, v39
	v_fma_f32 v28, v28, v32, 0
	v_fma_f32 v29, v29, v33, 0
	v_fma_f32 v30, v30, v34, 0
	v_fma_f32 v31, v31, v35, 0
	v_fma_f32 v27, v27, v39, 0
	v_fma_f32 v32, v24, v36, 0
	v_fma_f32 v33, v25, v37, 0
	v_fma_f32 v34, v26, v38, 0
	v_cvt_pk_bf16_f32 v24, v28, v29
	v_cvt_pk_bf16_f32 v25, v30, v31
	v_cvt_pk_bf16_f32 v26, v32, v33
	v_cvt_pk_bf16_f32 v27, v34, v27
	global_load_dwordx4 v[28:31], v[52:53], off offset:256
	v_add_u32_e32 v32, 0xb0, v144
	v_lshlrev_b64 v[34:35], 12, v[48:49]
	v_ashrrev_i32_e32 v33, 31, v32
	v_lshl_add_u64 v[34:35], s[14:15], 0, v[34:35]
	v_lshlrev_b64 v[36:37], 13, v[32:33]
	v_lshl_add_u64 v[34:35], v[34:35], 0, v[142:143]
	v_lshl_add_u64 v[36:37], s[16:17], 0, v[36:37]
	global_store_dwordx4 v[34:35], v[24:27], off
	v_lshl_add_u64 v[36:37], v[36:37], 0, v[142:143]
	s_waitcnt vmcnt(1)
	v_lshlrev_b32_e32 v24, 16, v28
	v_and_b32_e32 v25, 0xffff0000, v28
	v_lshlrev_b32_e32 v26, 16, v29
	v_and_b32_e32 v27, 0xffff0000, v29
	v_lshlrev_b32_e32 v28, 16, v30
	v_and_b32_e32 v29, 0xffff0000, v30
	v_lshlrev_b32_e32 v30, 16, v31
	v_and_b32_e32 v31, 0xffff0000, v31
	v_fma_f32 v20, v20, v24, 0
	v_fma_f32 v21, v21, v25, 0
	v_fma_f32 v22, v22, v26, 0
	v_fma_f32 v23, v23, v27, 0
	v_fma_f32 v19, v19, v31, 0
	v_fma_f32 v24, v16, v28, 0
	v_fma_f32 v25, v17, v29, 0
	v_fma_f32 v26, v18, v30, 0
	v_cvt_pk_bf16_f32 v16, v20, v21
	v_cvt_pk_bf16_f32 v17, v22, v23
	v_cvt_pk_bf16_f32 v18, v24, v25
	v_cvt_pk_bf16_f32 v19, v26, v19
	global_load_dwordx4 v[20:23], v[36:37], off
	s_nop 0
	global_store_dwordx4 v[34:35], v[16:19], off offset:256
	s_waitcnt vmcnt(1)
	s_nop 0
	v_lshlrev_b32_e32 v16, 16, v20
	v_and_b32_e32 v17, 0xffff0000, v20
	v_lshlrev_b32_e32 v18, 16, v21
	v_and_b32_e32 v19, 0xffff0000, v21
	v_lshlrev_b32_e32 v20, 16, v22
	v_and_b32_e32 v21, 0xffff0000, v22
	v_lshlrev_b32_e32 v22, 16, v23
	v_and_b32_e32 v23, 0xffff0000, v23
	v_fma_f32 v12, v12, v16, 0
	v_fma_f32 v13, v13, v17, 0
	v_fma_f32 v14, v14, v18, 0
	v_fma_f32 v15, v15, v19, 0
	v_fma_f32 v11, v11, v23, 0
	v_fma_f32 v16, v8, v20, 0
	v_fma_f32 v17, v9, v21, 0
	v_fma_f32 v18, v10, v22, 0
	v_cvt_pk_bf16_f32 v8, v12, v13
	v_cvt_pk_bf16_f32 v9, v14, v15
	v_cvt_pk_bf16_f32 v10, v16, v17
	v_cvt_pk_bf16_f32 v11, v18, v11
	global_load_dwordx4 v[12:15], v[36:37], off offset:256
	v_lshlrev_b64 v[16:17], 12, v[32:33]
	v_lshl_add_u64 v[16:17], s[14:15], 0, v[16:17]
	v_lshl_add_u64 v[16:17], v[16:17], 0, v[142:143]
	global_store_dwordx4 v[16:17], v[8:11], off
	s_waitcnt vmcnt(1)
	s_nop 0
	v_lshlrev_b32_e32 v8, 16, v12
	v_and_b32_e32 v9, 0xffff0000, v12
	v_lshlrev_b32_e32 v10, 16, v13
	v_and_b32_e32 v11, 0xffff0000, v13
	v_lshlrev_b32_e32 v12, 16, v14
	v_and_b32_e32 v13, 0xffff0000, v14
	v_lshlrev_b32_e32 v14, 16, v15
	v_and_b32_e32 v15, 0xffff0000, v15
	v_fma_f32 v3, v3, v15, 0
	v_fma_f32 v4, v4, v8, 0
	v_fma_f32 v5, v5, v9, 0
	v_fma_f32 v6, v6, v10, 0
	v_fma_f32 v7, v7, v11, 0
	v_fma_f32 v8, v0, v12, 0
	v_fma_f32 v9, v1, v13, 0
	v_fma_f32 v10, v2, v14, 0
	v_cvt_pk_bf16_f32 v0, v4, v5
	v_cvt_pk_bf16_f32 v1, v6, v7
	v_cvt_pk_bf16_f32 v2, v8, v9
	v_cvt_pk_bf16_f32 v3, v10, v3
	global_store_dwordx4 v[16:17], v[0:3], off offset:256
	s_cbranch_vccnz .LBB0_1170
	s_andn2_b64 vcc, exec, s[12:13]
	s_cbranch_vccnz .LBB0_1169
	s_barrier
	s_branch .LBB0_1169

.LBB0_1261:
	s_lshl_b32 s0, s65, 8
	v_mov_b32_e32 v142, v147
	v_mov_b32_e32 v143, v146
	s_add_i32 s0, s0, s55
	s_nop 0
	v_add_u32_e32 v144, s0, v142
	s_lshl_b32 s0, s64, 8
	s_or_b32 s0, s0, s56
	v_lshl_add_u32 v142, v143, 3, s0
	v_ashrrev_i32_e32 v145, 31, v144
	v_lshlrev_b64 v[152:153], 13, v[144:145]
	v_ashrrev_i32_e32 v143, 31, v142
	v_lshl_add_u64 v[152:153], s[16:17], 0, v[152:153]
	v_lshlrev_b64 v[142:143], 1, v[142:143]
	v_lshl_add_u64 v[160:161], v[152:153], 0, v[142:143]
	v_lshlrev_b64 v[156:157], 12, v[144:145]
	v_add_co_u32_e32 v152, vcc, s61, v160
	v_lshl_add_u64 v[156:157], s[14:15], 0, v[156:157]
	s_nop 0
	v_addc_co_u32_e32 v153, vcc, 0, v161, vcc
	v_lshl_add_u64 v[162:163], v[156:157], 0, v[142:143]
	global_load_dwordx4 v[152:155], v[152:153], off
	v_lshl_add_u64 v[160:161], v[160:161], 0, s[24:25]
	global_load_dwordx4 v[156:159], v[162:163], off
	s_waitcnt vmcnt(0)
	v_lshlrev_b32_e32 v145, 16, v152
	v_and_b32_e32 v152, 0xffff0000, v152
	v_lshlrev_b32_e32 v164, 16, v153
	v_and_b32_e32 v153, 0xffff0000, v153
	v_lshlrev_b32_e32 v165, 16, v154
	v_and_b32_e32 v154, 0xffff0000, v154
	v_lshlrev_b32_e32 v166, 16, v155
	v_and_b32_e32 v155, 0xffff0000, v155
	v_lshlrev_b32_e32 v167, 16, v156
	v_and_b32_e32 v156, 0xffff0000, v156
	v_lshlrev_b32_e32 v168, 16, v157
	v_and_b32_e32 v157, 0xffff0000, v157
	v_lshlrev_b32_e32 v169, 16, v158
	v_and_b32_e32 v158, 0xffff0000, v158
	v_lshlrev_b32_e32 v170, 16, v159
	v_and_b32_e32 v159, 0xffff0000, v159
	v_fmac_f32_e32 v167, v124, v145
	v_fmac_f32_e32 v156, v125, v152
	v_fmac_f32_e32 v168, v126, v164
	v_fmac_f32_e32 v157, v127, v153
	v_fmac_f32_e32 v169, v120, v165
	v_fmac_f32_e32 v158, v121, v154
	v_fmac_f32_e32 v170, v122, v166
	v_fmac_f32_e32 v159, v123, v155
	v_cvt_pk_bf16_f32 v120, v167, v156
	v_cvt_pk_bf16_f32 v121, v168, v157
	v_cvt_pk_bf16_f32 v122, v169, v158
	v_cvt_pk_bf16_f32 v123, v170, v159
	global_load_dwordx4 v[124:127], v[160:161], off offset:256
	global_load_dwordx4 v[152:155], v[162:163], off offset:256
	v_add_u32_e32 v156, 16, v144
	v_ashrrev_i32_e32 v157, 31, v156
	v_lshlrev_b64 v[158:159], 13, v[156:157]
	v_lshl_add_u64 v[158:159], s[16:17], 0, v[158:159]
	global_store_dwordx4 v[162:163], v[120:123], off
	v_lshl_add_u64 v[158:159], v[158:159], 0, v[142:143]
	v_add_co_u32_e32 v160, vcc, s61, v158
	s_waitcnt vmcnt(1)
	v_lshlrev_b32_e32 v120, 16, v124
	v_and_b32_e32 v121, 0xffff0000, v124
	v_lshlrev_b32_e32 v145, 16, v152
	v_and_b32_e32 v152, 0xffff0000, v152
	v_fmac_f32_e32 v145, v116, v120
	v_fmac_f32_e32 v152, v117, v121
	v_lshlrev_b64 v[120:121], 12, v[156:157]
	v_lshlrev_b32_e32 v122, 16, v125
	v_and_b32_e32 v123, 0xffff0000, v125
	v_lshlrev_b32_e32 v124, 16, v126
	v_and_b32_e32 v125, 0xffff0000, v126
	v_lshlrev_b32_e32 v165, 16, v154
	v_and_b32_e32 v154, 0xffff0000, v154
	v_lshl_add_u64 v[120:121], s[14:15], 0, v[120:121]
	v_addc_co_u32_e32 v161, vcc, 0, v159, vcc
	v_lshlrev_b32_e32 v126, 16, v127
	v_and_b32_e32 v127, 0xffff0000, v127
	v_lshlrev_b32_e32 v164, 16, v153
	v_and_b32_e32 v153, 0xffff0000, v153
	v_lshlrev_b32_e32 v166, 16, v155
	v_and_b32_e32 v155, 0xffff0000, v155
	v_fmac_f32_e32 v165, v112, v124
	v_fmac_f32_e32 v154, v113, v125
	v_lshl_add_u64 v[124:125], v[120:121], 0, v[142:143]
	v_fmac_f32_e32 v164, v118, v122
	v_fmac_f32_e32 v153, v119, v123
	v_fmac_f32_e32 v166, v114, v126
	v_fmac_f32_e32 v155, v115, v127
	v_cvt_pk_bf16_f32 v112, v145, v152
	v_cvt_pk_bf16_f32 v113, v164, v153
	v_cvt_pk_bf16_f32 v114, v165, v154
	v_cvt_pk_bf16_f32 v115, v166, v155
	global_load_dwordx4 v[116:119], v[160:161], off
	global_load_dwordx4 v[120:123], v[124:125], off
	v_lshl_add_u64 v[126:127], v[158:159], 0, s[24:25]
	global_store_dwordx4 v[162:163], v[112:115], off offset:256
	s_waitcnt vmcnt(1)
	v_lshlrev_b32_e32 v145, 16, v120
	v_lshlrev_b32_e32 v112, 16, v116
	v_and_b32_e32 v113, 0xffff0000, v116
	v_lshlrev_b32_e32 v114, 16, v117
	v_and_b32_e32 v115, 0xffff0000, v117
	v_lshlrev_b32_e32 v116, 16, v118
	v_and_b32_e32 v117, 0xffff0000, v118
	v_lshlrev_b32_e32 v118, 16, v119
	v_and_b32_e32 v119, 0xffff0000, v119
	v_and_b32_e32 v120, 0xffff0000, v120
	v_lshlrev_b32_e32 v152, 16, v121
	v_and_b32_e32 v121, 0xffff0000, v121
	v_lshlrev_b32_e32 v153, 16, v122
	v_and_b32_e32 v122, 0xffff0000, v122
	v_lshlrev_b32_e32 v154, 16, v123
	v_and_b32_e32 v123, 0xffff0000, v123
	v_fmac_f32_e32 v145, v108, v112
	v_fmac_f32_e32 v120, v109, v113
	v_fmac_f32_e32 v152, v110, v114
	v_fmac_f32_e32 v121, v111, v115
	v_fmac_f32_e32 v153, v104, v116
	v_fmac_f32_e32 v122, v105, v117
	v_fmac_f32_e32 v154, v106, v118
	v_fmac_f32_e32 v123, v107, v119
	v_cvt_pk_bf16_f32 v104, v145, v120
	v_cvt_pk_bf16_f32 v105, v152, v121
	v_cvt_pk_bf16_f32 v106, v153, v122
	v_cvt_pk_bf16_f32 v107, v154, v123
	global_load_dwordx4 v[108:111], v[126:127], off offset:256
	global_load_dwordx4 v[112:115], v[124:125], off offset:256
	v_add_u32_e32 v116, 32, v144
	v_ashrrev_i32_e32 v117, 31, v116
	v_lshlrev_b64 v[118:119], 13, v[116:117]
	v_lshl_add_u64 v[118:119], s[16:17], 0, v[118:119]
	global_store_dwordx4 v[124:125], v[104:107], off
	v_lshl_add_u64 v[118:119], v[118:119], 0, v[142:143]
	v_add_co_u32_e32 v120, vcc, s61, v118
	s_waitcnt vmcnt(1)
	v_lshlrev_b32_e32 v104, 16, v108
	v_and_b32_e32 v105, 0xffff0000, v108
	v_lshlrev_b32_e32 v122, 16, v112
	v_and_b32_e32 v112, 0xffff0000, v112
	v_fmac_f32_e32 v122, v100, v104
	v_fmac_f32_e32 v112, v101, v105
	v_lshlrev_b64 v[104:105], 12, v[116:117]
	v_lshlrev_b32_e32 v106, 16, v109
	v_and_b32_e32 v107, 0xffff0000, v109
	v_lshlrev_b32_e32 v108, 16, v110
	v_and_b32_e32 v109, 0xffff0000, v110
	v_lshlrev_b32_e32 v126, 16, v114
	v_and_b32_e32 v114, 0xffff0000, v114
	v_lshl_add_u64 v[104:105], s[14:15], 0, v[104:105]
	v_addc_co_u32_e32 v121, vcc, 0, v119, vcc
	v_lshlrev_b32_e32 v110, 16, v111
	v_and_b32_e32 v111, 0xffff0000, v111
	v_lshlrev_b32_e32 v123, 16, v113
	v_and_b32_e32 v113, 0xffff0000, v113
	v_lshlrev_b32_e32 v127, 16, v115
	v_and_b32_e32 v115, 0xffff0000, v115
	v_fmac_f32_e32 v126, v96, v108
	v_fmac_f32_e32 v114, v97, v109
	v_lshl_add_u64 v[108:109], v[104:105], 0, v[142:143]
	v_fmac_f32_e32 v123, v102, v106
	v_fmac_f32_e32 v113, v103, v107
	v_fmac_f32_e32 v127, v98, v110
	v_fmac_f32_e32 v115, v99, v111
	v_cvt_pk_bf16_f32 v96, v122, v112
	v_cvt_pk_bf16_f32 v97, v123, v113
	v_cvt_pk_bf16_f32 v98, v126, v114
	v_cvt_pk_bf16_f32 v99, v127, v115
	global_load_dwordx4 v[100:103], v[120:121], off
	global_load_dwordx4 v[104:107], v[108:109], off
	v_lshl_add_u64 v[110:111], v[118:119], 0, s[24:25]
	global_store_dwordx4 v[124:125], v[96:99], off offset:256
	s_waitcnt vmcnt(1)
	v_lshlrev_b32_e32 v112, 16, v104
	v_lshlrev_b32_e32 v96, 16, v100
	v_and_b32_e32 v97, 0xffff0000, v100
	v_lshlrev_b32_e32 v98, 16, v101
	v_and_b32_e32 v99, 0xffff0000, v101
	v_lshlrev_b32_e32 v100, 16, v102
	v_and_b32_e32 v101, 0xffff0000, v102
	v_lshlrev_b32_e32 v102, 16, v103
	v_and_b32_e32 v103, 0xffff0000, v103
	v_and_b32_e32 v104, 0xffff0000, v104
	v_lshlrev_b32_e32 v113, 16, v105
	v_and_b32_e32 v105, 0xffff0000, v105
	v_lshlrev_b32_e32 v114, 16, v106
	v_and_b32_e32 v106, 0xffff0000, v106
	v_lshlrev_b32_e32 v115, 16, v107
	v_and_b32_e32 v107, 0xffff0000, v107
	v_fmac_f32_e32 v112, v92, v96
	v_fmac_f32_e32 v104, v93, v97
	v_fmac_f32_e32 v113, v94, v98
	v_fmac_f32_e32 v105, v95, v99
	v_fmac_f32_e32 v114, v88, v100
	v_fmac_f32_e32 v106, v89, v101
	v_fmac_f32_e32 v115, v90, v102
	v_fmac_f32_e32 v107, v91, v103
	v_cvt_pk_bf16_f32 v88, v112, v104
	v_cvt_pk_bf16_f32 v89, v113, v105
	v_cvt_pk_bf16_f32 v90, v114, v106
	v_cvt_pk_bf16_f32 v91, v115, v107
	global_load_dwordx4 v[92:95], v[110:111], off offset:256
	global_load_dwordx4 v[96:99], v[108:109], off offset:256
	v_add_u32_e32 v100, 48, v144
	v_ashrrev_i32_e32 v101, 31, v100
	v_lshlrev_b64 v[102:103], 13, v[100:101]
	v_lshl_add_u64 v[102:103], s[16:17], 0, v[102:103]
	global_store_dwordx4 v[108:109], v[88:91], off
	v_lshl_add_u64 v[102:103], v[102:103], 0, v[142:143]
	v_add_co_u32_e32 v104, vcc, s61, v102
	s_waitcnt vmcnt(1)
	v_lshlrev_b32_e32 v88, 16, v92
	v_and_b32_e32 v89, 0xffff0000, v92
	v_lshlrev_b32_e32 v106, 16, v96
	v_and_b32_e32 v96, 0xffff0000, v96
	v_fmac_f32_e32 v106, v84, v88
	v_fmac_f32_e32 v96, v85, v89
	v_lshlrev_b64 v[88:89], 12, v[100:101]
	v_lshlrev_b32_e32 v90, 16, v93
	v_and_b32_e32 v91, 0xffff0000, v93
	v_lshlrev_b32_e32 v92, 16, v94
	v_and_b32_e32 v93, 0xffff0000, v94
	v_lshlrev_b32_e32 v110, 16, v98
	v_and_b32_e32 v98, 0xffff0000, v98
	v_lshl_add_u64 v[88:89], s[14:15], 0, v[88:89]
	v_addc_co_u32_e32 v105, vcc, 0, v103, vcc
	v_lshlrev_b32_e32 v94, 16, v95
	v_and_b32_e32 v95, 0xffff0000, v95
	v_lshlrev_b32_e32 v107, 16, v97
	v_and_b32_e32 v97, 0xffff0000, v97
	v_lshlrev_b32_e32 v111, 16, v99
	v_and_b32_e32 v99, 0xffff0000, v99
	v_fmac_f32_e32 v110, v80, v92
	v_fmac_f32_e32 v98, v81, v93
	v_lshl_add_u64 v[92:93], v[88:89], 0, v[142:143]
	v_fmac_f32_e32 v107, v86, v90
	v_fmac_f32_e32 v97, v87, v91
	v_fmac_f32_e32 v111, v82, v94
	v_fmac_f32_e32 v99, v83, v95
	v_cvt_pk_bf16_f32 v80, v106, v96
	v_cvt_pk_bf16_f32 v81, v107, v97
	v_cvt_pk_bf16_f32 v82, v110, v98
	v_cvt_pk_bf16_f32 v83, v111, v99
	global_load_dwordx4 v[84:87], v[104:105], off
	global_load_dwordx4 v[88:91], v[92:93], off
	v_lshl_add_u64 v[94:95], v[102:103], 0, s[24:25]
	global_store_dwordx4 v[108:109], v[80:83], off offset:256
	s_waitcnt vmcnt(1)
	v_lshlrev_b32_e32 v96, 16, v88
	v_lshlrev_b32_e32 v80, 16, v84
	v_and_b32_e32 v81, 0xffff0000, v84
	v_lshlrev_b32_e32 v82, 16, v85
	v_and_b32_e32 v83, 0xffff0000, v85
	v_lshlrev_b32_e32 v84, 16, v86
	v_and_b32_e32 v85, 0xffff0000, v86
	v_lshlrev_b32_e32 v86, 16, v87
	v_and_b32_e32 v87, 0xffff0000, v87
	v_and_b32_e32 v88, 0xffff0000, v88
	v_lshlrev_b32_e32 v97, 16, v89
	v_and_b32_e32 v89, 0xffff0000, v89
	v_lshlrev_b32_e32 v98, 16, v90
	v_and_b32_e32 v90, 0xffff0000, v90
	v_lshlrev_b32_e32 v99, 16, v91
	v_and_b32_e32 v91, 0xffff0000, v91
	v_fmac_f32_e32 v96, v76, v80
	v_fmac_f32_e32 v88, v77, v81
	v_fmac_f32_e32 v97, v78, v82
	v_fmac_f32_e32 v89, v79, v83
	v_fmac_f32_e32 v98, v72, v84
	v_fmac_f32_e32 v90, v73, v85
	v_fmac_f32_e32 v99, v74, v86
	v_fmac_f32_e32 v91, v75, v87
	v_cvt_pk_bf16_f32 v72, v96, v88
	v_cvt_pk_bf16_f32 v73, v97, v89
	v_cvt_pk_bf16_f32 v74, v98, v90
	v_cvt_pk_bf16_f32 v75, v99, v91
	global_load_dwordx4 v[76:79], v[94:95], off offset:256
	global_load_dwordx4 v[80:83], v[92:93], off offset:256
	v_add_u32_e32 v84, 0x80, v144
	v_ashrrev_i32_e32 v85, 31, v84
	v_lshlrev_b64 v[86:87], 13, v[84:85]
	v_lshl_add_u64 v[86:87], s[16:17], 0, v[86:87]
	global_store_dwordx4 v[92:93], v[72:75], off
	v_lshl_add_u64 v[86:87], v[86:87], 0, v[142:143]
	v_add_co_u32_e32 v88, vcc, s61, v86
	s_waitcnt vmcnt(1)
	v_lshlrev_b32_e32 v72, 16, v76
	v_and_b32_e32 v73, 0xffff0000, v76
	v_lshlrev_b32_e32 v90, 16, v80
	v_and_b32_e32 v80, 0xffff0000, v80
	v_fmac_f32_e32 v90, v68, v72
	v_fmac_f32_e32 v80, v69, v73
	v_lshlrev_b64 v[72:73], 12, v[84:85]
	v_lshlrev_b32_e32 v74, 16, v77
	v_and_b32_e32 v75, 0xffff0000, v77
	v_lshlrev_b32_e32 v76, 16, v78
	v_and_b32_e32 v77, 0xffff0000, v78
	v_lshlrev_b32_e32 v94, 16, v82
	v_and_b32_e32 v82, 0xffff0000, v82
	v_lshl_add_u64 v[72:73], s[14:15], 0, v[72:73]
	v_addc_co_u32_e32 v89, vcc, 0, v87, vcc
	v_lshlrev_b32_e32 v78, 16, v79
	v_and_b32_e32 v79, 0xffff0000, v79
	v_lshlrev_b32_e32 v91, 16, v81
	v_and_b32_e32 v81, 0xffff0000, v81
	v_lshlrev_b32_e32 v95, 16, v83
	v_and_b32_e32 v83, 0xffff0000, v83
	v_fmac_f32_e32 v94, v64, v76
	v_fmac_f32_e32 v82, v65, v77
	v_lshl_add_u64 v[76:77], v[72:73], 0, v[142:143]
	v_fmac_f32_e32 v91, v70, v74
	v_fmac_f32_e32 v81, v71, v75
	v_fmac_f32_e32 v95, v66, v78
	v_fmac_f32_e32 v83, v67, v79
	v_cvt_pk_bf16_f32 v64, v90, v80
	v_cvt_pk_bf16_f32 v65, v91, v81
	v_cvt_pk_bf16_f32 v66, v94, v82
	v_cvt_pk_bf16_f32 v67, v95, v83
	global_load_dwordx4 v[68:71], v[88:89], off
	global_load_dwordx4 v[72:75], v[76:77], off
	v_lshl_add_u64 v[78:79], v[86:87], 0, s[24:25]
	global_store_dwordx4 v[92:93], v[64:67], off offset:256
	s_waitcnt vmcnt(1)
	v_lshlrev_b32_e32 v80, 16, v72
	v_lshlrev_b32_e32 v64, 16, v68
	v_and_b32_e32 v65, 0xffff0000, v68
	v_lshlrev_b32_e32 v66, 16, v69
	v_and_b32_e32 v67, 0xffff0000, v69
	v_lshlrev_b32_e32 v68, 16, v70
	v_and_b32_e32 v69, 0xffff0000, v70
	v_lshlrev_b32_e32 v70, 16, v71
	v_and_b32_e32 v71, 0xffff0000, v71
	v_and_b32_e32 v72, 0xffff0000, v72
	v_lshlrev_b32_e32 v81, 16, v73
	v_and_b32_e32 v73, 0xffff0000, v73
	v_lshlrev_b32_e32 v82, 16, v74
	v_and_b32_e32 v74, 0xffff0000, v74
	v_lshlrev_b32_e32 v83, 16, v75
	v_and_b32_e32 v75, 0xffff0000, v75
	v_fmac_f32_e32 v80, v60, v64
	v_fmac_f32_e32 v72, v61, v65
	v_fmac_f32_e32 v81, v62, v66
	v_fmac_f32_e32 v73, v63, v67
	v_fmac_f32_e32 v82, v56, v68
	v_fmac_f32_e32 v74, v57, v69
	v_fmac_f32_e32 v83, v58, v70
	v_fmac_f32_e32 v75, v59, v71
	v_cvt_pk_bf16_f32 v56, v80, v72
	v_cvt_pk_bf16_f32 v57, v81, v73
	v_cvt_pk_bf16_f32 v58, v82, v74
	v_cvt_pk_bf16_f32 v59, v83, v75
	global_load_dwordx4 v[60:63], v[78:79], off offset:256
	global_load_dwordx4 v[64:67], v[76:77], off offset:256
	v_add_u32_e32 v68, 0x90, v144
	v_ashrrev_i32_e32 v69, 31, v68
	v_lshlrev_b64 v[70:71], 13, v[68:69]
	v_lshl_add_u64 v[70:71], s[16:17], 0, v[70:71]
	global_store_dwordx4 v[76:77], v[56:59], off
	v_lshl_add_u64 v[70:71], v[70:71], 0, v[142:143]
	v_add_co_u32_e32 v72, vcc, s61, v70
	s_waitcnt vmcnt(1)
	v_lshlrev_b32_e32 v56, 16, v60
	v_and_b32_e32 v57, 0xffff0000, v60
	v_lshlrev_b32_e32 v74, 16, v64
	v_and_b32_e32 v64, 0xffff0000, v64
	v_fmac_f32_e32 v74, v52, v56
	v_fmac_f32_e32 v64, v53, v57
	v_lshlrev_b64 v[56:57], 12, v[68:69]
	v_lshlrev_b32_e32 v58, 16, v61
	v_and_b32_e32 v59, 0xffff0000, v61
	v_lshlrev_b32_e32 v60, 16, v62
	v_and_b32_e32 v61, 0xffff0000, v62
	v_lshlrev_b32_e32 v78, 16, v66
	v_and_b32_e32 v66, 0xffff0000, v66
	v_lshl_add_u64 v[56:57], s[14:15], 0, v[56:57]
	v_addc_co_u32_e32 v73, vcc, 0, v71, vcc
	v_lshlrev_b32_e32 v62, 16, v63
	v_and_b32_e32 v63, 0xffff0000, v63
	v_lshlrev_b32_e32 v75, 16, v65
	v_and_b32_e32 v65, 0xffff0000, v65
	v_lshlrev_b32_e32 v79, 16, v67
	v_and_b32_e32 v67, 0xffff0000, v67
	v_fmac_f32_e32 v78, v48, v60
	v_fmac_f32_e32 v66, v49, v61
	v_lshl_add_u64 v[60:61], v[56:57], 0, v[142:143]
	v_fmac_f32_e32 v75, v54, v58
	v_fmac_f32_e32 v65, v55, v59
	v_fmac_f32_e32 v79, v50, v62
	v_fmac_f32_e32 v67, v51, v63
	v_cvt_pk_bf16_f32 v48, v74, v64
	v_cvt_pk_bf16_f32 v49, v75, v65
	v_cvt_pk_bf16_f32 v50, v78, v66
	v_cvt_pk_bf16_f32 v51, v79, v67
	global_load_dwordx4 v[52:55], v[72:73], off
	global_load_dwordx4 v[56:59], v[60:61], off
	v_lshl_add_u64 v[62:63], v[70:71], 0, s[24:25]
	global_store_dwordx4 v[76:77], v[48:51], off offset:256
	s_waitcnt vmcnt(1)
	v_lshlrev_b32_e32 v64, 16, v56
	v_lshlrev_b32_e32 v48, 16, v52
	v_and_b32_e32 v49, 0xffff0000, v52
	v_lshlrev_b32_e32 v50, 16, v53
	v_and_b32_e32 v51, 0xffff0000, v53
	v_lshlrev_b32_e32 v52, 16, v54
	v_and_b32_e32 v53, 0xffff0000, v54
	v_lshlrev_b32_e32 v54, 16, v55
	v_and_b32_e32 v55, 0xffff0000, v55
	v_and_b32_e32 v56, 0xffff0000, v56
	v_lshlrev_b32_e32 v65, 16, v57
	v_and_b32_e32 v57, 0xffff0000, v57
	v_lshlrev_b32_e32 v66, 16, v58
	v_and_b32_e32 v58, 0xffff0000, v58
	v_lshlrev_b32_e32 v67, 16, v59
	v_and_b32_e32 v59, 0xffff0000, v59
	v_fmac_f32_e32 v64, v44, v48
	v_fmac_f32_e32 v56, v45, v49
	v_fmac_f32_e32 v65, v46, v50
	v_fmac_f32_e32 v57, v47, v51
	v_fmac_f32_e32 v66, v40, v52
	v_fmac_f32_e32 v58, v41, v53
	v_fmac_f32_e32 v67, v42, v54
	v_fmac_f32_e32 v59, v43, v55
	v_cvt_pk_bf16_f32 v40, v64, v56
	v_cvt_pk_bf16_f32 v41, v65, v57
	v_cvt_pk_bf16_f32 v42, v66, v58
	v_cvt_pk_bf16_f32 v43, v67, v59
	global_load_dwordx4 v[44:47], v[62:63], off offset:256
	global_load_dwordx4 v[48:51], v[60:61], off offset:256
	v_add_u32_e32 v52, 0xa0, v144
	v_ashrrev_i32_e32 v53, 31, v52
	v_lshlrev_b64 v[54:55], 13, v[52:53]
	v_lshl_add_u64 v[54:55], s[16:17], 0, v[54:55]
	global_store_dwordx4 v[60:61], v[40:43], off
	v_lshl_add_u64 v[54:55], v[54:55], 0, v[142:143]
	v_add_co_u32_e32 v56, vcc, s61, v54
	s_waitcnt vmcnt(1)
	v_lshlrev_b32_e32 v40, 16, v44
	v_and_b32_e32 v41, 0xffff0000, v44
	v_lshlrev_b32_e32 v58, 16, v48
	v_and_b32_e32 v48, 0xffff0000, v48
	v_fmac_f32_e32 v58, v36, v40
	v_fmac_f32_e32 v48, v37, v41
	v_lshlrev_b64 v[40:41], 12, v[52:53]
	v_lshlrev_b32_e32 v42, 16, v45
	v_and_b32_e32 v43, 0xffff0000, v45
	v_lshlrev_b32_e32 v44, 16, v46
	v_and_b32_e32 v45, 0xffff0000, v46
	v_lshlrev_b32_e32 v62, 16, v50
	v_and_b32_e32 v50, 0xffff0000, v50
	v_lshl_add_u64 v[40:41], s[14:15], 0, v[40:41]
	v_addc_co_u32_e32 v57, vcc, 0, v55, vcc
	v_lshlrev_b32_e32 v46, 16, v47
	v_and_b32_e32 v47, 0xffff0000, v47
	v_lshlrev_b32_e32 v59, 16, v49
	v_and_b32_e32 v49, 0xffff0000, v49
	v_lshlrev_b32_e32 v63, 16, v51
	v_and_b32_e32 v51, 0xffff0000, v51
	v_fmac_f32_e32 v62, v32, v44
	v_fmac_f32_e32 v50, v33, v45
	v_lshl_add_u64 v[44:45], v[40:41], 0, v[142:143]
	v_fmac_f32_e32 v59, v38, v42
	v_fmac_f32_e32 v49, v39, v43
	v_fmac_f32_e32 v63, v34, v46
	v_fmac_f32_e32 v51, v35, v47
	v_cvt_pk_bf16_f32 v32, v58, v48
	v_cvt_pk_bf16_f32 v33, v59, v49
	v_cvt_pk_bf16_f32 v34, v62, v50
	v_cvt_pk_bf16_f32 v35, v63, v51
	global_load_dwordx4 v[36:39], v[56:57], off
	global_load_dwordx4 v[40:43], v[44:45], off
	v_lshl_add_u64 v[46:47], v[54:55], 0, s[24:25]
	global_store_dwordx4 v[60:61], v[32:35], off offset:256
	s_waitcnt vmcnt(1)
	v_lshlrev_b32_e32 v48, 16, v40
	v_lshlrev_b32_e32 v32, 16, v36
	v_and_b32_e32 v33, 0xffff0000, v36
	v_lshlrev_b32_e32 v34, 16, v37
	v_and_b32_e32 v35, 0xffff0000, v37
	v_lshlrev_b32_e32 v36, 16, v38
	v_and_b32_e32 v37, 0xffff0000, v38
	v_lshlrev_b32_e32 v38, 16, v39
	v_and_b32_e32 v39, 0xffff0000, v39
	v_and_b32_e32 v40, 0xffff0000, v40
	v_lshlrev_b32_e32 v49, 16, v41
	v_and_b32_e32 v41, 0xffff0000, v41
	v_lshlrev_b32_e32 v50, 16, v42
	v_and_b32_e32 v42, 0xffff0000, v42
	v_lshlrev_b32_e32 v51, 16, v43
	v_and_b32_e32 v43, 0xffff0000, v43
	v_fmac_f32_e32 v48, v28, v32
	v_fmac_f32_e32 v40, v29, v33
	v_fmac_f32_e32 v49, v30, v34
	v_fmac_f32_e32 v41, v31, v35
	v_fmac_f32_e32 v50, v24, v36
	v_fmac_f32_e32 v42, v25, v37
	v_fmac_f32_e32 v51, v26, v38
	v_fmac_f32_e32 v43, v27, v39
	v_cvt_pk_bf16_f32 v24, v48, v40
	v_cvt_pk_bf16_f32 v25, v49, v41
	v_cvt_pk_bf16_f32 v26, v50, v42
	v_cvt_pk_bf16_f32 v27, v51, v43
	global_load_dwordx4 v[28:31], v[46:47], off offset:256
	global_load_dwordx4 v[32:35], v[44:45], off offset:256
	v_add_u32_e32 v36, 0xb0, v144
	v_ashrrev_i32_e32 v37, 31, v36
	v_lshlrev_b64 v[38:39], 13, v[36:37]
	v_lshl_add_u64 v[38:39], s[16:17], 0, v[38:39]
	global_store_dwordx4 v[44:45], v[24:27], off
	v_lshl_add_u64 v[38:39], v[38:39], 0, v[142:143]
	v_add_co_u32_e32 v40, vcc, s61, v38
	s_waitcnt vmcnt(1)
	v_lshlrev_b32_e32 v24, 16, v28
	v_and_b32_e32 v25, 0xffff0000, v28
	v_lshlrev_b32_e32 v42, 16, v32
	v_and_b32_e32 v32, 0xffff0000, v32
	v_fmac_f32_e32 v42, v20, v24
	v_fmac_f32_e32 v32, v21, v25
	v_lshlrev_b64 v[24:25], 12, v[36:37]
	v_lshlrev_b32_e32 v26, 16, v29
	v_and_b32_e32 v27, 0xffff0000, v29
	v_lshlrev_b32_e32 v28, 16, v30
	v_and_b32_e32 v29, 0xffff0000, v30
	v_lshlrev_b32_e32 v46, 16, v34
	v_and_b32_e32 v34, 0xffff0000, v34
	v_lshl_add_u64 v[24:25], s[14:15], 0, v[24:25]
	v_addc_co_u32_e32 v41, vcc, 0, v39, vcc
	v_lshlrev_b32_e32 v30, 16, v31
	v_and_b32_e32 v31, 0xffff0000, v31
	v_lshlrev_b32_e32 v43, 16, v33
	v_and_b32_e32 v33, 0xffff0000, v33
	v_lshlrev_b32_e32 v47, 16, v35
	v_and_b32_e32 v35, 0xffff0000, v35
	v_fmac_f32_e32 v46, v16, v28
	v_fmac_f32_e32 v34, v17, v29
	v_lshl_add_u64 v[28:29], v[24:25], 0, v[142:143]
	v_fmac_f32_e32 v43, v22, v26
	v_fmac_f32_e32 v33, v23, v27
	v_fmac_f32_e32 v47, v18, v30
	v_fmac_f32_e32 v35, v19, v31
	v_cvt_pk_bf16_f32 v16, v42, v32
	v_cvt_pk_bf16_f32 v17, v43, v33
	v_cvt_pk_bf16_f32 v18, v46, v34
	v_cvt_pk_bf16_f32 v19, v47, v35
	global_load_dwordx4 v[20:23], v[40:41], off
	global_load_dwordx4 v[24:27], v[28:29], off
	v_lshl_add_u64 v[30:31], v[38:39], 0, s[24:25]
	global_store_dwordx4 v[44:45], v[16:19], off offset:256
	s_and_b64 vcc, exec, s[2:3]
	s_mov_b64 s[2:3], -1
	s_waitcnt vmcnt(1)
	v_lshlrev_b32_e32 v16, 16, v20
	v_and_b32_e32 v17, 0xffff0000, v20
	v_lshlrev_b32_e32 v18, 16, v21
	v_and_b32_e32 v19, 0xffff0000, v21
	v_lshlrev_b32_e32 v20, 16, v22
	v_and_b32_e32 v21, 0xffff0000, v22
	v_lshlrev_b32_e32 v22, 16, v23
	v_and_b32_e32 v23, 0xffff0000, v23
	v_lshlrev_b32_e32 v32, 16, v24
	v_and_b32_e32 v24, 0xffff0000, v24
	v_lshlrev_b32_e32 v33, 16, v25
	v_and_b32_e32 v25, 0xffff0000, v25
	v_lshlrev_b32_e32 v34, 16, v26
	v_and_b32_e32 v26, 0xffff0000, v26
	v_lshlrev_b32_e32 v35, 16, v27
	v_and_b32_e32 v27, 0xffff0000, v27
	v_fmac_f32_e32 v32, v12, v16
	v_fmac_f32_e32 v24, v13, v17
	v_fmac_f32_e32 v33, v14, v18
	v_fmac_f32_e32 v25, v15, v19
	v_fmac_f32_e32 v34, v8, v20
	v_fmac_f32_e32 v26, v9, v21
	v_fmac_f32_e32 v35, v10, v22
	v_fmac_f32_e32 v27, v11, v23
	v_cvt_pk_bf16_f32 v8, v32, v24
	v_cvt_pk_bf16_f32 v9, v33, v25
	v_cvt_pk_bf16_f32 v10, v34, v26
	v_cvt_pk_bf16_f32 v11, v35, v27
	global_load_dwordx4 v[12:15], v[30:31], off offset:256
	global_load_dwordx4 v[16:19], v[28:29], off offset:256
	s_waitcnt vmcnt(0)
	v_lshlrev_b32_e32 v20, 16, v16
	global_store_dwordx4 v[28:29], v[8:11], off
	v_and_b32_e32 v16, 0xffff0000, v16
	v_lshlrev_b32_e32 v21, 16, v17
	v_lshlrev_b32_e32 v8, 16, v12
	v_and_b32_e32 v9, 0xffff0000, v12
	v_lshlrev_b32_e32 v10, 16, v13
	v_and_b32_e32 v11, 0xffff0000, v13
	v_lshlrev_b32_e32 v12, 16, v14
	v_and_b32_e32 v13, 0xffff0000, v14
	v_lshlrev_b32_e32 v14, 16, v15
	v_and_b32_e32 v15, 0xffff0000, v15
	v_and_b32_e32 v17, 0xffff0000, v17
	v_lshlrev_b32_e32 v22, 16, v18
	v_and_b32_e32 v18, 0xffff0000, v18
	v_lshlrev_b32_e32 v23, 16, v19
	v_and_b32_e32 v19, 0xffff0000, v19
	v_fmac_f32_e32 v20, v4, v8
	v_fmac_f32_e32 v16, v5, v9
	v_fmac_f32_e32 v21, v6, v10
	v_fmac_f32_e32 v17, v7, v11
	v_fmac_f32_e32 v22, v0, v12
	v_fmac_f32_e32 v18, v1, v13
	v_fmac_f32_e32 v23, v2, v14
	v_fmac_f32_e32 v19, v3, v15
	v_cvt_pk_bf16_f32 v0, v20, v16
	v_cvt_pk_bf16_f32 v1, v21, v17
	v_cvt_pk_bf16_f32 v2, v22, v18
	v_cvt_pk_bf16_f32 v3, v23, v19
	global_store_dwordx4 v[28:29], v[0:3], off offset:256
	s_cbranch_vccnz .LBB0_1249
	s_andn2_b64 vcc, exec, s[12:13]
	s_cbranch_vccnz .LBB0_1248
	s_barrier
	s_branch .LBB0_1248

.LBB0_1498:
	v_mov_b32_e32 v142, v147
	v_mov_b32_e32 v153, v146
	s_lshl_b32 s0, s63, 8
	s_add_i32 s0, s0, s53
	v_add_u32_e32 v142, s0, v142
	v_ashrrev_i32_e32 v143, 31, v142
	v_lshl_add_u64 v[144:145], v[142:143], 2, s[18:19]
	global_load_dword v152, v[144:145], off
	global_load_dword v233, v[144:145], off offset:64
	global_load_dword v234, v[144:145], off offset:128
	global_load_dword v235, v[144:145], off offset:192
	global_load_dword v236, v[144:145], off offset:512
	global_load_dword v237, v[144:145], off offset:576
	global_load_dword v238, v[144:145], off offset:640
	global_load_dword v239, v[144:145], off offset:704
	v_mov_b32_e32 v154, v124
	v_mov_b32_e32 v155, v120
	v_mov_b32_e32 v120, v125
	v_mov_b32_e32 v124, v126
	v_mov_b32_e32 v125, v122
	v_mov_b32_e32 v122, v127
	v_mov_b32_e32 v126, v116
	v_mov_b32_e32 v127, v112
	s_lshl_b32 s0, s62, 7
	s_or_b32 s0, s0, s54
	v_lshl_add_u32 v156, v153, 3, s0
	v_ashrrev_i32_e32 v157, 31, v156
	s_waitcnt vmcnt(0)
	v_pk_mul_f32 v[154:155], v[154:155], v[152:153] op_sel_hi:[1,0]
	v_pk_mul_f32 v[120:121], v[120:121], v[152:153] op_sel_hi:[1,0]
	v_mul_f32_e32 v112, 0xbfb8aa3b, v155
	v_pk_mul_f32 v[124:125], v[124:125], v[152:153] op_sel_hi:[1,0]
	v_pk_mul_f32 v[126:127], v[126:127], v[152:153] op_sel_hi:[1,0]
	v_mul_f32_e32 v116, 0xbfb8aa3b, v121
	v_exp_f32_e32 v112, v112
	v_pk_mul_f32 v[122:123], v[122:123], v[152:153] op_sel_hi:[1,0]
	v_mul_f32_e32 v143, 0xbfb8aa3b, v125
	v_mul_f32_e32 v158, 0xbfb8aa3b, v127
	v_exp_f32_e32 v116, v116
	v_mul_f32_e32 v153, 0xbfb8aa3b, v123
	v_exp_f32_e32 v143, v143
	v_exp_f32_e32 v158, v158
	v_exp_f32_e32 v153, v153
	v_add_f32_e32 v112, 1.0, v112
	v_add_f32_e32 v116, 1.0, v116
	v_div_scale_f32 v159, s[0:1], v112, v112, 1.0
	v_add_f32_e32 v143, 1.0, v143
	v_add_f32_e32 v158, 1.0, v158
	v_div_scale_f32 v161, s[0:1], v116, v116, 1.0
	v_rcp_f32_e32 v168, v159
	v_add_f32_e32 v153, 1.0, v153
	v_div_scale_f32 v163, s[0:1], v143, v143, 1.0
	v_div_scale_f32 v167, s[0:1], v158, v158, 1.0
	v_rcp_f32_e32 v169, v161
	v_div_scale_f32 v165, s[0:1], v153, v153, 1.0
	v_rcp_f32_e32 v170, v163
	v_rcp_f32_e32 v172, v167
	v_rcp_f32_e32 v171, v165
	v_fma_f32 v173, -v159, v168, 1.0
	v_div_scale_f32 v160, vcc, 1.0, v112, 1.0
	v_fma_f32 v174, -v161, v169, 1.0
	v_fmac_f32_e32 v168, v173, v168
	v_div_scale_f32 v162, s[4:5], 1.0, v116, 1.0
	v_fma_f32 v175, -v163, v170, 1.0
	v_fma_f32 v177, -v167, v172, 1.0
	v_fmac_f32_e32 v169, v174, v169
	v_mul_f32_e32 v173, v160, v168
	v_div_scale_f32 v164, s[6:7], 1.0, v143, 1.0
	v_fma_f32 v176, -v165, v171, 1.0
	v_fmac_f32_e32 v170, v175, v170
	v_fmac_f32_e32 v172, v177, v172
	v_mul_f32_e32 v174, v162, v169
	v_fma_f32 v177, -v159, v173, v160
	v_div_scale_f32 v166, s[8:9], 1.0, v153, 1.0
	v_fmac_f32_e32 v171, v176, v171
	v_mul_f32_e32 v175, v164, v170
	v_fma_f32 v178, -v161, v174, v162
	v_fmac_f32_e32 v173, v177, v168
	v_mul_f32_e32 v176, v166, v171
	v_fma_f32 v179, -v163, v175, v164
	v_fmac_f32_e32 v174, v178, v169
	v_fma_f32 v159, -v159, v173, v160
	v_fma_f32 v180, -v165, v176, v166
	v_fmac_f32_e32 v175, v179, v170
	v_fma_f32 v160, -v161, v174, v162
	v_div_fmas_f32 v159, v159, v168, v173
	s_mov_b64 vcc, s[4:5]
	v_fmac_f32_e32 v176, v180, v171
	v_fma_f32 v161, -v163, v175, v164
	v_div_fixup_f32 v112, v159, v112, 1.0
	v_div_fmas_f32 v159, v160, v169, v174
	s_mov_b64 vcc, s[6:7]
	v_fma_f32 v162, -v165, v176, v166
	v_mul_f32_e32 v112, v155, v112
	v_div_fixup_f32 v116, v159, v116, 1.0
	v_div_fmas_f32 v155, v161, v170, v175
	s_mov_b64 vcc, s[8:9]
	v_mul_f32_e32 v154, v154, v112
	v_mul_f32_e32 v112, v121, v116
	v_div_fixup_f32 v116, v155, v143, 1.0
	v_div_fmas_f32 v121, v162, v171, v176
	v_mul_f32_e32 v120, v120, v112
	v_mul_f32_e32 v112, v125, v116
	v_div_fixup_f32 v116, v121, v153, 1.0
	v_mul_f32_e32 v121, v124, v112
	v_mul_f32_e32 v112, v123, v116
	v_div_scale_f32 v116, vcc, 1.0, v158, 1.0
	v_mul_f32_e32 v123, v116, v172
	v_mul_f32_e32 v122, v122, v112
	v_fma_f32 v112, -v167, v123, v116
	v_fmac_f32_e32 v123, v112, v172
	v_mov_b32_e32 v112, v117
	v_pk_mul_f32 v[112:113], v[112:113], v[152:153] op_sel_hi:[1,0]
	v_fma_f32 v116, -v167, v123, v116
	v_mul_f32_e32 v117, 0xbfb8aa3b, v113
	v_exp_f32_e32 v117, v117
	v_div_fmas_f32 v116, v116, v172, v123
	v_div_fixup_f32 v116, v116, v158, 1.0
	v_mul_f32_e32 v116, v127, v116
	v_add_f32_e32 v123, 1.0, v117
	v_div_scale_f32 v124, s[0:1], v123, v123, 1.0
	v_rcp_f32_e32 v125, v124
	v_mul_f32_e32 v126, v126, v116
	v_div_scale_f32 v127, vcc, 1.0, v123, 1.0
	v_fma_f32 v116, -v124, v125, 1.0
	v_fmac_f32_e32 v125, v116, v125
	v_mul_f32_e32 v143, v127, v125
	v_fma_f32 v116, -v124, v143, v127
	v_fmac_f32_e32 v143, v116, v125
	v_mov_b32_e32 v116, v118
	v_mov_b32_e32 v117, v114
	v_pk_mul_f32 v[116:117], v[116:117], v[152:153] op_sel_hi:[1,0]
	v_fma_f32 v118, -v124, v143, v127
	v_mul_f32_e32 v114, 0xbfb8aa3b, v117
	v_exp_f32_e32 v114, v114
	v_div_fmas_f32 v118, v118, v125, v143
	v_add_f32_e32 v124, 1.0, v114
	v_div_scale_f32 v125, s[0:1], v124, v124, 1.0
	v_rcp_f32_e32 v127, v125
	v_div_fixup_f32 v114, v118, v123, 1.0
	v_mul_f32_e32 v113, v113, v114
	v_mul_f32_e32 v118, v112, v113
	v_fma_f32 v112, -v125, v127, 1.0
	v_fmac_f32_e32 v127, v112, v127
	v_div_scale_f32 v123, vcc, 1.0, v124, 1.0
	v_mul_f32_e32 v143, v123, v127
	v_fma_f32 v112, -v125, v143, v123
	v_mov_b32_e32 v114, v119
	v_fmac_f32_e32 v143, v112, v127
	v_pk_mul_f32 v[112:113], v[114:115], v[152:153] op_sel_hi:[1,0]
	v_fma_f32 v115, -v125, v143, v123
	v_mul_f32_e32 v114, 0xbfb8aa3b, v113
	v_exp_f32_e32 v114, v114
	v_div_fmas_f32 v115, v115, v127, v143
	v_div_fixup_f32 v115, v115, v124, 1.0
	v_mul_f32_e32 v115, v117, v115
	v_add_f32_e32 v114, 1.0, v114
	v_div_scale_f32 v119, s[0:1], v114, v114, 1.0
	v_rcp_f32_e32 v123, v119
	v_mul_f32_e32 v115, v116, v115
	v_fma_f32 v116, -v119, v123, 1.0
	v_fmac_f32_e32 v123, v116, v123
	v_div_scale_f32 v116, vcc, 1.0, v114, 1.0
	v_mul_f32_e32 v117, v116, v123
	v_fma_f32 v124, -v119, v117, v116
	v_fmac_f32_e32 v117, v124, v123
	v_fma_f32 v116, -v119, v117, v116
	v_div_fmas_f32 v116, v116, v123, v117
	v_div_fixup_f32 v114, v116, v114, 1.0
	v_mul_f32_e32 v113, v113, v114
	v_mul_f32_e32 v112, v112, v113
	v_cvt_pk_bf16_f32 v116, v154, v120
	v_cvt_pk_bf16_f32 v117, v121, v122
	v_cvt_pk_bf16_f32 v118, v126, v118
	v_cvt_pk_bf16_f32 v119, v115, v112
	v_mov_b64_e32 v[112:113], s[10:11]
	v_mad_i64_i32 v[120:121], s[0:1], v142, s59, v[112:113]
	v_lshlrev_b64 v[114:115], 1, v[156:157]
	v_lshl_add_u64 v[120:121], v[120:121], 0, v[114:115]
	global_store_dwordx4 v[120:121], v[116:119], off
	s_nop 0
	v_add_u32_e32 v121, 16, v142
	v_mov_b32_e32 v118, v108
	v_mov_b32_e32 v119, v104
	v_mov_b32_e32 v116, v233
	v_pk_mul_f32 v[118:119], v[118:119], v[116:117] op_sel_hi:[1,0]
	s_nop 0
	v_mul_f32_e32 v104, 0xbfb8aa3b, v119
	v_exp_f32_e32 v104, v104
	s_nop 0
	v_add_f32_e32 v108, 1.0, v104
	v_div_scale_f32 v117, s[0:1], v108, v108, 1.0
	v_rcp_f32_e32 v120, v117
	v_div_scale_f32 v122, vcc, 1.0, v108, 1.0
	v_fma_f32 v104, -v117, v120, 1.0
	v_fmac_f32_e32 v120, v104, v120
	v_mul_f32_e32 v123, v122, v120
	v_fma_f32 v104, -v117, v123, v122
	v_fmac_f32_e32 v123, v104, v120
	v_mov_b32_e32 v104, v109
	v_pk_mul_f32 v[104:105], v[104:105], v[116:117] op_sel_hi:[1,0]
	v_fma_f32 v117, -v117, v123, v122
	v_mul_f32_e32 v109, 0xbfb8aa3b, v105
	v_exp_f32_e32 v109, v109
	v_div_fmas_f32 v117, v117, v120, v123
	v_div_fixup_f32 v108, v117, v108, 1.0
	v_mul_f32_e32 v108, v119, v108
	v_add_f32_e32 v120, 1.0, v109
	v_div_scale_f32 v122, s[0:1], v120, v120, 1.0
	v_rcp_f32_e32 v123, v122
	v_mul_f32_e32 v117, v118, v108
	v_div_scale_f32 v118, vcc, 1.0, v120, 1.0
	v_fma_f32 v108, -v122, v123, 1.0
	v_fmac_f32_e32 v123, v108, v123
	v_mul_f32_e32 v119, v118, v123
	v_fma_f32 v108, -v122, v119, v118
	v_fmac_f32_e32 v119, v108, v123
	v_mov_b32_e32 v108, v110
	v_mov_b32_e32 v109, v106
	v_pk_mul_f32 v[108:109], v[108:109], v[116:117] op_sel_hi:[1,0]
	v_fma_f32 v110, -v122, v119, v118
	v_mul_f32_e32 v106, 0xbfb8aa3b, v109
	v_exp_f32_e32 v106, v106
	v_div_fmas_f32 v110, v110, v123, v119
	v_add_f32_e32 v118, 1.0, v106
	v_div_scale_f32 v119, s[0:1], v118, v118, 1.0
	v_rcp_f32_e32 v122, v119
	v_div_fixup_f32 v106, v110, v120, 1.0
	v_mul_f32_e32 v105, v105, v106
	v_mul_f32_e32 v110, v104, v105
	v_fma_f32 v104, -v119, v122, 1.0
	v_fmac_f32_e32 v122, v104, v122
	v_div_scale_f32 v120, vcc, 1.0, v118, 1.0
	v_mul_f32_e32 v123, v120, v122
	v_fma_f32 v104, -v119, v123, v120
	v_mov_b32_e32 v106, v111
	v_fmac_f32_e32 v123, v104, v122
	v_pk_mul_f32 v[104:105], v[106:107], v[116:117] op_sel_hi:[1,0]
	v_fma_f32 v107, -v119, v123, v120
	v_mul_f32_e32 v106, 0xbfb8aa3b, v105
	v_exp_f32_e32 v106, v106
	v_div_fmas_f32 v107, v107, v122, v123
	v_add_f32_e32 v111, 1.0, v106
	v_div_scale_f32 v119, s[0:1], v111, v111, 1.0
	v_rcp_f32_e32 v120, v119
	v_div_fixup_f32 v106, v107, v118, 1.0
	v_mul_f32_e32 v106, v109, v106
	v_mul_f32_e32 v108, v108, v106
	v_fma_f32 v106, -v119, v120, 1.0
	v_fmac_f32_e32 v120, v106, v120
	v_div_scale_f32 v109, vcc, 1.0, v111, 1.0
	v_mul_f32_e32 v118, v109, v120
	v_fma_f32 v106, -v119, v118, v109
	v_fmac_f32_e32 v118, v106, v120
	v_mov_b32_e32 v106, v100
	v_mov_b32_e32 v107, v96
	v_pk_mul_f32 v[106:107], v[106:107], v[116:117] op_sel_hi:[1,0]
	v_fma_f32 v100, -v119, v118, v109
	v_mul_f32_e32 v96, 0xbfb8aa3b, v107
	v_exp_f32_e32 v96, v96
	v_div_fmas_f32 v100, v100, v120, v118
	v_add_f32_e32 v109, 1.0, v96
	v_div_scale_f32 v118, s[0:1], v109, v109, 1.0
	v_rcp_f32_e32 v119, v118
	v_div_fixup_f32 v96, v100, v111, 1.0
	v_mul_f32_e32 v96, v105, v96
	v_mul_f32_e32 v104, v104, v96
	v_fma_f32 v96, -v118, v119, 1.0
	v_fmac_f32_e32 v119, v96, v119
	v_div_scale_f32 v100, vcc, 1.0, v109, 1.0
	v_mul_f32_e32 v105, v100, v119
	v_fma_f32 v96, -v118, v105, v100
	v_fmac_f32_e32 v105, v96, v119
	v_mov_b32_e32 v96, v101
	v_pk_mul_f32 v[96:97], v[96:97], v[116:117] op_sel_hi:[1,0]
	v_fma_f32 v100, -v118, v105, v100
	v_mul_f32_e32 v101, 0xbfb8aa3b, v97
	v_exp_f32_e32 v101, v101
	v_div_fmas_f32 v100, v100, v119, v105
	v_div_fixup_f32 v100, v100, v109, 1.0
	v_mul_f32_e32 v100, v107, v100
	v_add_f32_e32 v105, 1.0, v101
	v_div_scale_f32 v111, s[0:1], v105, v105, 1.0
	v_rcp_f32_e32 v118, v111
	v_mul_f32_e32 v106, v106, v100
	v_div_scale_f32 v107, vcc, 1.0, v105, 1.0
	v_fma_f32 v100, -v111, v118, 1.0
	v_fmac_f32_e32 v118, v100, v118
	v_mul_f32_e32 v109, v107, v118
	v_fma_f32 v100, -v111, v109, v107
	v_fmac_f32_e32 v109, v100, v118
	v_mov_b32_e32 v100, v102
	v_mov_b32_e32 v101, v98
	v_pk_mul_f32 v[100:101], v[100:101], v[116:117] op_sel_hi:[1,0]
	v_fma_f32 v102, -v111, v109, v107
	v_mul_f32_e32 v98, 0xbfb8aa3b, v101
	v_exp_f32_e32 v98, v98
	v_div_fmas_f32 v102, v102, v118, v109
	v_add_f32_e32 v107, 1.0, v98
	v_div_scale_f32 v109, s[0:1], v107, v107, 1.0
	v_rcp_f32_e32 v111, v109
	v_div_fixup_f32 v98, v102, v105, 1.0
	v_mul_f32_e32 v97, v97, v98
	v_mul_f32_e32 v102, v96, v97
	v_fma_f32 v96, -v109, v111, 1.0
	v_fmac_f32_e32 v111, v96, v111
	v_div_scale_f32 v105, vcc, 1.0, v107, 1.0
	v_mul_f32_e32 v118, v105, v111
	v_fma_f32 v96, -v109, v118, v105
	v_mov_b32_e32 v98, v103
	v_fmac_f32_e32 v118, v96, v111
	v_pk_mul_f32 v[96:97], v[98:99], v[116:117] op_sel_hi:[1,0]
	v_fma_f32 v99, -v109, v118, v105
	v_mul_f32_e32 v98, 0xbfb8aa3b, v97
	v_exp_f32_e32 v98, v98
	v_div_fmas_f32 v99, v99, v111, v118
	v_div_fixup_f32 v99, v99, v107, 1.0
	v_mul_f32_e32 v99, v101, v99
	v_add_f32_e32 v98, 1.0, v98
	v_div_scale_f32 v103, s[0:1], v98, v98, 1.0
	v_rcp_f32_e32 v105, v103
	v_mul_f32_e32 v99, v100, v99
	v_fma_f32 v100, -v103, v105, 1.0
	v_fmac_f32_e32 v105, v100, v105
	v_div_scale_f32 v100, vcc, 1.0, v98, 1.0
	v_mul_f32_e32 v101, v100, v105
	v_fma_f32 v107, -v103, v101, v100
	v_fmac_f32_e32 v101, v107, v105
	v_fma_f32 v100, -v103, v101, v100
	v_div_fmas_f32 v100, v100, v105, v101
	v_div_fixup_f32 v98, v100, v98, 1.0
	v_mul_f32_e32 v97, v97, v98
	v_mul_f32_e32 v100, v96, v97
	v_cvt_pk_bf16_f32 v96, v117, v110
	v_cvt_pk_bf16_f32 v97, v108, v104
	v_cvt_pk_bf16_f32 v98, v106, v102
	v_cvt_pk_bf16_f32 v99, v99, v100
	v_mad_i64_i32 v[100:101], s[0:1], v121, s59, v[112:113]
	v_lshl_add_u64 v[100:101], v[100:101], 0, v[114:115]
	global_store_dwordx4 v[100:101], v[96:99], off
	s_nop 0
	v_add_u32_e32 v101, 32, v142
	v_mov_b32_e32 v98, v92
	v_mov_b32_e32 v99, v88
	v_mov_b32_e32 v96, v234
	v_pk_mul_f32 v[98:99], v[98:99], v[96:97] op_sel_hi:[1,0]
	s_nop 0
	v_mul_f32_e32 v88, 0xbfb8aa3b, v99
	v_exp_f32_e32 v88, v88
	s_nop 0
	v_add_f32_e32 v92, 1.0, v88
	v_div_scale_f32 v97, s[0:1], v92, v92, 1.0
	v_rcp_f32_e32 v100, v97
	v_div_scale_f32 v102, vcc, 1.0, v92, 1.0
	v_fma_f32 v88, -v97, v100, 1.0
	v_fmac_f32_e32 v100, v88, v100
	v_mul_f32_e32 v103, v102, v100
	v_fma_f32 v88, -v97, v103, v102
	v_fmac_f32_e32 v103, v88, v100
	v_mov_b32_e32 v88, v93
	v_pk_mul_f32 v[88:89], v[88:89], v[96:97] op_sel_hi:[1,0]
	v_fma_f32 v97, -v97, v103, v102
	v_mul_f32_e32 v93, 0xbfb8aa3b, v89
	v_exp_f32_e32 v93, v93
	v_div_fmas_f32 v97, v97, v100, v103
	v_div_fixup_f32 v92, v97, v92, 1.0
	v_mul_f32_e32 v92, v99, v92
	v_add_f32_e32 v100, 1.0, v93
	v_div_scale_f32 v102, s[0:1], v100, v100, 1.0
	v_rcp_f32_e32 v103, v102
	v_mul_f32_e32 v97, v98, v92
	v_div_scale_f32 v98, vcc, 1.0, v100, 1.0
	v_fma_f32 v92, -v102, v103, 1.0
	v_fmac_f32_e32 v103, v92, v103
	v_mul_f32_e32 v99, v98, v103
	v_fma_f32 v92, -v102, v99, v98
	v_fmac_f32_e32 v99, v92, v103
	v_mov_b32_e32 v92, v94
	v_mov_b32_e32 v93, v90
	v_pk_mul_f32 v[92:93], v[92:93], v[96:97] op_sel_hi:[1,0]
	v_fma_f32 v94, -v102, v99, v98
	v_mul_f32_e32 v90, 0xbfb8aa3b, v93
	v_exp_f32_e32 v90, v90
	v_div_fmas_f32 v94, v94, v103, v99
	v_add_f32_e32 v98, 1.0, v90
	v_div_scale_f32 v99, s[0:1], v98, v98, 1.0
	v_rcp_f32_e32 v102, v99
	v_div_fixup_f32 v90, v94, v100, 1.0
	v_mul_f32_e32 v89, v89, v90
	v_mul_f32_e32 v94, v88, v89
	v_fma_f32 v88, -v99, v102, 1.0
	v_fmac_f32_e32 v102, v88, v102
	v_div_scale_f32 v100, vcc, 1.0, v98, 1.0
	v_mul_f32_e32 v103, v100, v102
	v_fma_f32 v88, -v99, v103, v100
	v_mov_b32_e32 v90, v95
	v_fmac_f32_e32 v103, v88, v102
	v_pk_mul_f32 v[88:89], v[90:91], v[96:97] op_sel_hi:[1,0]
	v_fma_f32 v91, -v99, v103, v100
	v_mul_f32_e32 v90, 0xbfb8aa3b, v89
	v_exp_f32_e32 v90, v90
	v_div_fmas_f32 v91, v91, v102, v103
	v_add_f32_e32 v95, 1.0, v90
	v_div_scale_f32 v99, s[0:1], v95, v95, 1.0
	v_rcp_f32_e32 v100, v99
	v_div_fixup_f32 v90, v91, v98, 1.0
	v_mul_f32_e32 v90, v93, v90
	v_mul_f32_e32 v92, v92, v90
	v_fma_f32 v90, -v99, v100, 1.0
	v_fmac_f32_e32 v100, v90, v100
	v_div_scale_f32 v93, vcc, 1.0, v95, 1.0
	v_mul_f32_e32 v98, v93, v100
	v_fma_f32 v90, -v99, v98, v93
	v_fmac_f32_e32 v98, v90, v100
	v_mov_b32_e32 v90, v84
	v_mov_b32_e32 v91, v80
	v_pk_mul_f32 v[90:91], v[90:91], v[96:97] op_sel_hi:[1,0]
	v_fma_f32 v84, -v99, v98, v93
	v_mul_f32_e32 v80, 0xbfb8aa3b, v91
	v_exp_f32_e32 v80, v80
	v_div_fmas_f32 v84, v84, v100, v98
	v_add_f32_e32 v93, 1.0, v80
	v_div_scale_f32 v98, s[0:1], v93, v93, 1.0
	v_rcp_f32_e32 v99, v98
	v_div_fixup_f32 v80, v84, v95, 1.0
	v_mul_f32_e32 v80, v89, v80
	v_mul_f32_e32 v88, v88, v80
	v_fma_f32 v80, -v98, v99, 1.0
	v_fmac_f32_e32 v99, v80, v99
	v_div_scale_f32 v84, vcc, 1.0, v93, 1.0
	v_mul_f32_e32 v89, v84, v99
	v_fma_f32 v80, -v98, v89, v84
	v_fmac_f32_e32 v89, v80, v99
	v_mov_b32_e32 v80, v85
	v_pk_mul_f32 v[80:81], v[80:81], v[96:97] op_sel_hi:[1,0]
	v_fma_f32 v84, -v98, v89, v84
	v_mul_f32_e32 v85, 0xbfb8aa3b, v81
	v_exp_f32_e32 v85, v85
	v_div_fmas_f32 v84, v84, v99, v89
	v_div_fixup_f32 v84, v84, v93, 1.0
	v_mul_f32_e32 v84, v91, v84
	v_add_f32_e32 v89, 1.0, v85
	v_div_scale_f32 v95, s[0:1], v89, v89, 1.0
	v_rcp_f32_e32 v98, v95
	v_mul_f32_e32 v90, v90, v84
	v_div_scale_f32 v91, vcc, 1.0, v89, 1.0
	v_fma_f32 v84, -v95, v98, 1.0
	v_fmac_f32_e32 v98, v84, v98
	v_mul_f32_e32 v93, v91, v98
	v_fma_f32 v84, -v95, v93, v91
	v_fmac_f32_e32 v93, v84, v98
	v_mov_b32_e32 v84, v86
	v_mov_b32_e32 v85, v82
	v_pk_mul_f32 v[84:85], v[84:85], v[96:97] op_sel_hi:[1,0]
	v_fma_f32 v86, -v95, v93, v91
	v_mul_f32_e32 v82, 0xbfb8aa3b, v85
	v_exp_f32_e32 v82, v82
	v_div_fmas_f32 v86, v86, v98, v93
	v_add_f32_e32 v91, 1.0, v82
	v_div_scale_f32 v93, s[0:1], v91, v91, 1.0
	v_rcp_f32_e32 v95, v93
	v_div_fixup_f32 v82, v86, v89, 1.0
	v_mul_f32_e32 v81, v81, v82
	v_mul_f32_e32 v86, v80, v81
	v_fma_f32 v80, -v93, v95, 1.0
	v_fmac_f32_e32 v95, v80, v95
	v_div_scale_f32 v89, vcc, 1.0, v91, 1.0
	v_mul_f32_e32 v98, v89, v95
	v_fma_f32 v80, -v93, v98, v89
	v_mov_b32_e32 v82, v87
	v_fmac_f32_e32 v98, v80, v95
	v_pk_mul_f32 v[80:81], v[82:83], v[96:97] op_sel_hi:[1,0]
	v_fma_f32 v83, -v93, v98, v89
	v_mul_f32_e32 v82, 0xbfb8aa3b, v81
	v_exp_f32_e32 v82, v82
	v_div_fmas_f32 v83, v83, v95, v98
	v_div_fixup_f32 v83, v83, v91, 1.0
	v_mul_f32_e32 v83, v85, v83
	v_add_f32_e32 v82, 1.0, v82
	v_div_scale_f32 v87, s[0:1], v82, v82, 1.0
	v_rcp_f32_e32 v89, v87
	v_mul_f32_e32 v83, v84, v83
	v_fma_f32 v84, -v87, v89, 1.0
	v_fmac_f32_e32 v89, v84, v89
	v_div_scale_f32 v84, vcc, 1.0, v82, 1.0
	v_mul_f32_e32 v85, v84, v89
	v_fma_f32 v91, -v87, v85, v84
	v_fmac_f32_e32 v85, v91, v89
	v_fma_f32 v84, -v87, v85, v84
	v_div_fmas_f32 v84, v84, v89, v85
	v_div_fixup_f32 v82, v84, v82, 1.0
	v_mul_f32_e32 v81, v81, v82
	v_mul_f32_e32 v84, v80, v81
	v_cvt_pk_bf16_f32 v80, v97, v94
	v_cvt_pk_bf16_f32 v81, v92, v88
	v_cvt_pk_bf16_f32 v82, v90, v86
	v_cvt_pk_bf16_f32 v83, v83, v84
	v_mad_i64_i32 v[84:85], s[0:1], v101, s59, v[112:113]
	v_lshl_add_u64 v[84:85], v[84:85], 0, v[114:115]
	global_store_dwordx4 v[84:85], v[80:83], off
	s_nop 0
	v_add_u32_e32 v85, 48, v142
	v_mov_b32_e32 v82, v76
	v_mov_b32_e32 v83, v72
	v_mov_b32_e32 v80, v235
	v_pk_mul_f32 v[82:83], v[82:83], v[80:81] op_sel_hi:[1,0]
	s_nop 0
	v_mul_f32_e32 v72, 0xbfb8aa3b, v83
	v_exp_f32_e32 v72, v72
	s_nop 0
	v_add_f32_e32 v76, 1.0, v72
	v_div_scale_f32 v81, s[0:1], v76, v76, 1.0
	v_rcp_f32_e32 v84, v81
	v_div_scale_f32 v86, vcc, 1.0, v76, 1.0
	v_fma_f32 v72, -v81, v84, 1.0
	v_fmac_f32_e32 v84, v72, v84
	v_mul_f32_e32 v87, v86, v84
	v_fma_f32 v72, -v81, v87, v86
	v_fmac_f32_e32 v87, v72, v84
	v_mov_b32_e32 v72, v77
	v_pk_mul_f32 v[72:73], v[72:73], v[80:81] op_sel_hi:[1,0]
	v_fma_f32 v81, -v81, v87, v86
	v_mul_f32_e32 v77, 0xbfb8aa3b, v73
	v_exp_f32_e32 v77, v77
	v_div_fmas_f32 v81, v81, v84, v87
	v_div_fixup_f32 v76, v81, v76, 1.0
	v_mul_f32_e32 v76, v83, v76
	v_add_f32_e32 v84, 1.0, v77
	v_div_scale_f32 v86, s[0:1], v84, v84, 1.0
	v_rcp_f32_e32 v87, v86
	v_mul_f32_e32 v81, v82, v76
	v_div_scale_f32 v82, vcc, 1.0, v84, 1.0
	v_fma_f32 v76, -v86, v87, 1.0
	v_fmac_f32_e32 v87, v76, v87
	v_mul_f32_e32 v83, v82, v87
	v_fma_f32 v76, -v86, v83, v82
	v_fmac_f32_e32 v83, v76, v87
	v_mov_b32_e32 v76, v78
	v_mov_b32_e32 v77, v74
	v_pk_mul_f32 v[76:77], v[76:77], v[80:81] op_sel_hi:[1,0]
	v_fma_f32 v78, -v86, v83, v82
	v_mul_f32_e32 v74, 0xbfb8aa3b, v77
	v_exp_f32_e32 v74, v74
	v_div_fmas_f32 v78, v78, v87, v83
	v_add_f32_e32 v82, 1.0, v74
	v_div_scale_f32 v83, s[0:1], v82, v82, 1.0
	v_rcp_f32_e32 v86, v83
	v_div_fixup_f32 v74, v78, v84, 1.0
	v_mul_f32_e32 v73, v73, v74
	v_mul_f32_e32 v78, v72, v73
	v_fma_f32 v72, -v83, v86, 1.0
	v_fmac_f32_e32 v86, v72, v86
	v_div_scale_f32 v84, vcc, 1.0, v82, 1.0
	v_mul_f32_e32 v87, v84, v86
	v_fma_f32 v72, -v83, v87, v84
	v_mov_b32_e32 v74, v79
	v_fmac_f32_e32 v87, v72, v86
	v_pk_mul_f32 v[72:73], v[74:75], v[80:81] op_sel_hi:[1,0]
	v_fma_f32 v75, -v83, v87, v84
	v_mul_f32_e32 v74, 0xbfb8aa3b, v73
	v_exp_f32_e32 v74, v74
	v_div_fmas_f32 v75, v75, v86, v87
	v_add_f32_e32 v79, 1.0, v74
	v_div_scale_f32 v83, s[0:1], v79, v79, 1.0
	v_rcp_f32_e32 v84, v83
	v_div_fixup_f32 v74, v75, v82, 1.0
	v_mul_f32_e32 v74, v77, v74
	v_mul_f32_e32 v76, v76, v74
	v_fma_f32 v74, -v83, v84, 1.0
	v_fmac_f32_e32 v84, v74, v84
	v_div_scale_f32 v77, vcc, 1.0, v79, 1.0
	v_mul_f32_e32 v82, v77, v84
	v_fma_f32 v74, -v83, v82, v77
	v_fmac_f32_e32 v82, v74, v84
	v_mov_b32_e32 v74, v68
	v_mov_b32_e32 v75, v64
	v_pk_mul_f32 v[74:75], v[74:75], v[80:81] op_sel_hi:[1,0]
	v_fma_f32 v68, -v83, v82, v77
	v_mul_f32_e32 v64, 0xbfb8aa3b, v75
	v_exp_f32_e32 v64, v64
	v_div_fmas_f32 v68, v68, v84, v82
	v_add_f32_e32 v77, 1.0, v64
	v_div_scale_f32 v82, s[0:1], v77, v77, 1.0
	v_rcp_f32_e32 v83, v82
	v_div_fixup_f32 v64, v68, v79, 1.0
	v_mul_f32_e32 v64, v73, v64
	v_mul_f32_e32 v72, v72, v64
	v_fma_f32 v64, -v82, v83, 1.0
	v_fmac_f32_e32 v83, v64, v83
	v_div_scale_f32 v68, vcc, 1.0, v77, 1.0
	v_mul_f32_e32 v73, v68, v83
	v_fma_f32 v64, -v82, v73, v68
	v_fmac_f32_e32 v73, v64, v83
	v_mov_b32_e32 v64, v69
	v_pk_mul_f32 v[64:65], v[64:65], v[80:81] op_sel_hi:[1,0]
	v_fma_f32 v68, -v82, v73, v68
	v_mul_f32_e32 v69, 0xbfb8aa3b, v65
	v_exp_f32_e32 v69, v69
	v_div_fmas_f32 v68, v68, v83, v73
	v_div_fixup_f32 v68, v68, v77, 1.0
	v_mul_f32_e32 v68, v75, v68
	v_add_f32_e32 v73, 1.0, v69
	v_div_scale_f32 v79, s[0:1], v73, v73, 1.0
	v_rcp_f32_e32 v82, v79
	v_mul_f32_e32 v74, v74, v68
	v_div_scale_f32 v75, vcc, 1.0, v73, 1.0
	v_fma_f32 v68, -v79, v82, 1.0
	v_fmac_f32_e32 v82, v68, v82
	v_mul_f32_e32 v77, v75, v82
	v_fma_f32 v68, -v79, v77, v75
	v_fmac_f32_e32 v77, v68, v82
	v_mov_b32_e32 v68, v70
	v_mov_b32_e32 v69, v66
	v_pk_mul_f32 v[68:69], v[68:69], v[80:81] op_sel_hi:[1,0]
	v_fma_f32 v70, -v79, v77, v75
	v_mul_f32_e32 v66, 0xbfb8aa3b, v69
	v_exp_f32_e32 v66, v66
	v_div_fmas_f32 v70, v70, v82, v77
	v_add_f32_e32 v75, 1.0, v66
	v_div_scale_f32 v77, s[0:1], v75, v75, 1.0
	v_rcp_f32_e32 v79, v77
	v_div_fixup_f32 v66, v70, v73, 1.0
	v_mul_f32_e32 v65, v65, v66
	v_mul_f32_e32 v70, v64, v65
	v_fma_f32 v64, -v77, v79, 1.0
	v_fmac_f32_e32 v79, v64, v79
	v_div_scale_f32 v73, vcc, 1.0, v75, 1.0
	v_mul_f32_e32 v82, v73, v79
	v_fma_f32 v64, -v77, v82, v73
	v_mov_b32_e32 v66, v71
	v_fmac_f32_e32 v82, v64, v79
	v_pk_mul_f32 v[64:65], v[66:67], v[80:81] op_sel_hi:[1,0]
	v_fma_f32 v67, -v77, v82, v73
	v_mul_f32_e32 v66, 0xbfb8aa3b, v65
	v_exp_f32_e32 v66, v66
	v_div_fmas_f32 v67, v67, v79, v82
	v_div_fixup_f32 v67, v67, v75, 1.0
	v_mul_f32_e32 v67, v69, v67
	v_add_f32_e32 v66, 1.0, v66
	v_div_scale_f32 v71, s[0:1], v66, v66, 1.0
	v_rcp_f32_e32 v73, v71
	v_mul_f32_e32 v67, v68, v67
	v_fma_f32 v68, -v71, v73, 1.0
	v_fmac_f32_e32 v73, v68, v73
	v_div_scale_f32 v68, vcc, 1.0, v66, 1.0
	v_mul_f32_e32 v69, v68, v73
	v_fma_f32 v75, -v71, v69, v68
	v_fmac_f32_e32 v69, v75, v73
	v_fma_f32 v68, -v71, v69, v68
	v_div_fmas_f32 v68, v68, v73, v69
	v_div_fixup_f32 v66, v68, v66, 1.0
	v_mul_f32_e32 v65, v65, v66
	v_mul_f32_e32 v68, v64, v65
	v_cvt_pk_bf16_f32 v64, v81, v78
	v_cvt_pk_bf16_f32 v65, v76, v72
	v_cvt_pk_bf16_f32 v66, v74, v70
	v_cvt_pk_bf16_f32 v67, v67, v68
	v_mad_i64_i32 v[68:69], s[0:1], v85, s59, v[112:113]
	v_lshl_add_u64 v[68:69], v[68:69], 0, v[114:115]
	global_store_dwordx4 v[68:69], v[64:67], off
	s_nop 0
	v_add_u32_e32 v69, 0x80, v142
	v_mov_b32_e32 v66, v60
	v_mov_b32_e32 v67, v56
	v_mov_b32_e32 v64, v236
	v_pk_mul_f32 v[66:67], v[66:67], v[64:65] op_sel_hi:[1,0]
	s_nop 0
	v_mul_f32_e32 v56, 0xbfb8aa3b, v67
	v_exp_f32_e32 v56, v56
	s_nop 0
	v_add_f32_e32 v60, 1.0, v56
	v_div_scale_f32 v65, s[0:1], v60, v60, 1.0
	v_rcp_f32_e32 v68, v65
	v_div_scale_f32 v70, vcc, 1.0, v60, 1.0
	v_fma_f32 v56, -v65, v68, 1.0
	v_fmac_f32_e32 v68, v56, v68
	v_mul_f32_e32 v71, v70, v68
	v_fma_f32 v56, -v65, v71, v70
	v_fmac_f32_e32 v71, v56, v68
	v_mov_b32_e32 v56, v61
	v_pk_mul_f32 v[56:57], v[56:57], v[64:65] op_sel_hi:[1,0]
	v_fma_f32 v65, -v65, v71, v70
	v_mul_f32_e32 v61, 0xbfb8aa3b, v57
	v_exp_f32_e32 v61, v61
	v_div_fmas_f32 v65, v65, v68, v71
	v_div_fixup_f32 v60, v65, v60, 1.0
	v_mul_f32_e32 v60, v67, v60
	v_add_f32_e32 v68, 1.0, v61
	v_div_scale_f32 v70, s[0:1], v68, v68, 1.0
	v_rcp_f32_e32 v71, v70
	v_mul_f32_e32 v65, v66, v60
	v_div_scale_f32 v66, vcc, 1.0, v68, 1.0
	v_fma_f32 v60, -v70, v71, 1.0
	v_fmac_f32_e32 v71, v60, v71
	v_mul_f32_e32 v67, v66, v71
	v_fma_f32 v60, -v70, v67, v66
	v_fmac_f32_e32 v67, v60, v71
	v_mov_b32_e32 v60, v62
	v_mov_b32_e32 v61, v58
	v_pk_mul_f32 v[60:61], v[60:61], v[64:65] op_sel_hi:[1,0]
	v_fma_f32 v62, -v70, v67, v66
	v_mul_f32_e32 v58, 0xbfb8aa3b, v61
	v_exp_f32_e32 v58, v58
	v_div_fmas_f32 v62, v62, v71, v67
	v_add_f32_e32 v66, 1.0, v58
	v_div_scale_f32 v67, s[0:1], v66, v66, 1.0
	v_rcp_f32_e32 v70, v67
	v_div_fixup_f32 v58, v62, v68, 1.0
	v_mul_f32_e32 v57, v57, v58
	v_mul_f32_e32 v62, v56, v57
	v_fma_f32 v56, -v67, v70, 1.0
	v_fmac_f32_e32 v70, v56, v70
	v_div_scale_f32 v68, vcc, 1.0, v66, 1.0
	v_mul_f32_e32 v71, v68, v70
	v_fma_f32 v56, -v67, v71, v68
	v_mov_b32_e32 v58, v63
	v_fmac_f32_e32 v71, v56, v70
	v_pk_mul_f32 v[56:57], v[58:59], v[64:65] op_sel_hi:[1,0]
	v_fma_f32 v59, -v67, v71, v68
	v_mul_f32_e32 v58, 0xbfb8aa3b, v57
	v_exp_f32_e32 v58, v58
	v_div_fmas_f32 v59, v59, v70, v71
	v_add_f32_e32 v63, 1.0, v58
	v_div_scale_f32 v67, s[0:1], v63, v63, 1.0
	v_rcp_f32_e32 v68, v67
	v_div_fixup_f32 v58, v59, v66, 1.0
	v_mul_f32_e32 v58, v61, v58
	v_mul_f32_e32 v60, v60, v58
	v_fma_f32 v58, -v67, v68, 1.0
	v_fmac_f32_e32 v68, v58, v68
	v_div_scale_f32 v61, vcc, 1.0, v63, 1.0
	v_mul_f32_e32 v66, v61, v68
	v_fma_f32 v58, -v67, v66, v61
	v_fmac_f32_e32 v66, v58, v68
	v_mov_b32_e32 v58, v52
	v_mov_b32_e32 v59, v48
	v_pk_mul_f32 v[58:59], v[58:59], v[64:65] op_sel_hi:[1,0]
	v_fma_f32 v52, -v67, v66, v61
	v_mul_f32_e32 v48, 0xbfb8aa3b, v59
	v_exp_f32_e32 v48, v48
	v_div_fmas_f32 v52, v52, v68, v66
	v_add_f32_e32 v61, 1.0, v48
	v_div_scale_f32 v66, s[0:1], v61, v61, 1.0
	v_rcp_f32_e32 v67, v66
	v_div_fixup_f32 v48, v52, v63, 1.0
	v_mul_f32_e32 v48, v57, v48
	v_mul_f32_e32 v56, v56, v48
	v_fma_f32 v48, -v66, v67, 1.0
	v_fmac_f32_e32 v67, v48, v67
	v_div_scale_f32 v52, vcc, 1.0, v61, 1.0
	v_mul_f32_e32 v57, v52, v67
	v_fma_f32 v48, -v66, v57, v52
	v_fmac_f32_e32 v57, v48, v67
	v_mov_b32_e32 v48, v53
	v_pk_mul_f32 v[48:49], v[48:49], v[64:65] op_sel_hi:[1,0]
	v_fma_f32 v52, -v66, v57, v52
	v_mul_f32_e32 v53, 0xbfb8aa3b, v49
	v_exp_f32_e32 v53, v53
	v_div_fmas_f32 v52, v52, v67, v57
	v_div_fixup_f32 v52, v52, v61, 1.0
	v_mul_f32_e32 v52, v59, v52
	v_add_f32_e32 v57, 1.0, v53
	v_div_scale_f32 v63, s[0:1], v57, v57, 1.0
	v_rcp_f32_e32 v66, v63
	v_mul_f32_e32 v58, v58, v52
	v_div_scale_f32 v59, vcc, 1.0, v57, 1.0
	v_fma_f32 v52, -v63, v66, 1.0
	v_fmac_f32_e32 v66, v52, v66
	v_mul_f32_e32 v61, v59, v66
	v_fma_f32 v52, -v63, v61, v59
	v_fmac_f32_e32 v61, v52, v66
	v_mov_b32_e32 v52, v54
	v_mov_b32_e32 v53, v50
	v_pk_mul_f32 v[52:53], v[52:53], v[64:65] op_sel_hi:[1,0]
	v_fma_f32 v54, -v63, v61, v59
	v_mul_f32_e32 v50, 0xbfb8aa3b, v53
	v_exp_f32_e32 v50, v50
	v_div_fmas_f32 v54, v54, v66, v61
	v_add_f32_e32 v59, 1.0, v50
	v_div_scale_f32 v61, s[0:1], v59, v59, 1.0
	v_rcp_f32_e32 v63, v61
	v_div_fixup_f32 v50, v54, v57, 1.0
	v_mul_f32_e32 v49, v49, v50
	v_mul_f32_e32 v54, v48, v49
	v_fma_f32 v48, -v61, v63, 1.0
	v_fmac_f32_e32 v63, v48, v63
	v_div_scale_f32 v57, vcc, 1.0, v59, 1.0
	v_mul_f32_e32 v66, v57, v63
	v_fma_f32 v48, -v61, v66, v57
	v_mov_b32_e32 v50, v55
	v_fmac_f32_e32 v66, v48, v63
	v_pk_mul_f32 v[48:49], v[50:51], v[64:65] op_sel_hi:[1,0]
	v_fma_f32 v51, -v61, v66, v57
	v_mul_f32_e32 v50, 0xbfb8aa3b, v49
	v_exp_f32_e32 v50, v50
	v_div_fmas_f32 v51, v51, v63, v66
	v_div_fixup_f32 v51, v51, v59, 1.0
	v_mul_f32_e32 v51, v53, v51
	v_add_f32_e32 v50, 1.0, v50
	v_div_scale_f32 v55, s[0:1], v50, v50, 1.0
	v_rcp_f32_e32 v57, v55
	v_mul_f32_e32 v51, v52, v51
	v_fma_f32 v52, -v55, v57, 1.0
	v_fmac_f32_e32 v57, v52, v57
	v_div_scale_f32 v52, vcc, 1.0, v50, 1.0
	v_mul_f32_e32 v53, v52, v57
	v_fma_f32 v59, -v55, v53, v52
	v_fmac_f32_e32 v53, v59, v57
	v_fma_f32 v52, -v55, v53, v52
	v_div_fmas_f32 v52, v52, v57, v53
	v_div_fixup_f32 v50, v52, v50, 1.0
	v_mul_f32_e32 v49, v49, v50
	v_mul_f32_e32 v52, v48, v49
	v_cvt_pk_bf16_f32 v48, v65, v62
	v_cvt_pk_bf16_f32 v49, v60, v56
	v_cvt_pk_bf16_f32 v50, v58, v54
	v_cvt_pk_bf16_f32 v51, v51, v52
	v_mad_i64_i32 v[52:53], s[0:1], v69, s59, v[112:113]
	v_lshl_add_u64 v[52:53], v[52:53], 0, v[114:115]
	global_store_dwordx4 v[52:53], v[48:51], off
	s_nop 0
	v_add_u32_e32 v53, 0x90, v142
	v_mov_b32_e32 v50, v44
	v_mov_b32_e32 v51, v40
	v_mov_b32_e32 v48, v237
	v_pk_mul_f32 v[50:51], v[50:51], v[48:49] op_sel_hi:[1,0]
	s_nop 0
	v_mul_f32_e32 v40, 0xbfb8aa3b, v51
	v_exp_f32_e32 v40, v40
	s_nop 0
	v_add_f32_e32 v44, 1.0, v40
	v_div_scale_f32 v49, s[0:1], v44, v44, 1.0
	v_rcp_f32_e32 v52, v49
	v_div_scale_f32 v54, vcc, 1.0, v44, 1.0
	v_fma_f32 v40, -v49, v52, 1.0
	v_fmac_f32_e32 v52, v40, v52
	v_mul_f32_e32 v55, v54, v52
	v_fma_f32 v40, -v49, v55, v54
	v_fmac_f32_e32 v55, v40, v52
	v_mov_b32_e32 v40, v45
	v_pk_mul_f32 v[40:41], v[40:41], v[48:49] op_sel_hi:[1,0]
	v_fma_f32 v49, -v49, v55, v54
	v_mul_f32_e32 v45, 0xbfb8aa3b, v41
	v_exp_f32_e32 v45, v45
	v_div_fmas_f32 v49, v49, v52, v55
	v_div_fixup_f32 v44, v49, v44, 1.0
	v_mul_f32_e32 v44, v51, v44
	v_add_f32_e32 v52, 1.0, v45
	v_div_scale_f32 v54, s[0:1], v52, v52, 1.0
	v_rcp_f32_e32 v55, v54
	v_mul_f32_e32 v49, v50, v44
	v_div_scale_f32 v50, vcc, 1.0, v52, 1.0
	v_fma_f32 v44, -v54, v55, 1.0
	v_fmac_f32_e32 v55, v44, v55
	v_mul_f32_e32 v51, v50, v55
	v_fma_f32 v44, -v54, v51, v50
	v_fmac_f32_e32 v51, v44, v55
	v_mov_b32_e32 v44, v46
	v_mov_b32_e32 v45, v42
	v_pk_mul_f32 v[44:45], v[44:45], v[48:49] op_sel_hi:[1,0]
	v_fma_f32 v46, -v54, v51, v50
	v_mul_f32_e32 v42, 0xbfb8aa3b, v45
	v_exp_f32_e32 v42, v42
	v_div_fmas_f32 v46, v46, v55, v51
	v_add_f32_e32 v50, 1.0, v42
	v_div_scale_f32 v51, s[0:1], v50, v50, 1.0
	v_rcp_f32_e32 v54, v51
	v_div_fixup_f32 v42, v46, v52, 1.0
	v_mul_f32_e32 v41, v41, v42
	v_mul_f32_e32 v46, v40, v41
	v_fma_f32 v40, -v51, v54, 1.0
	v_fmac_f32_e32 v54, v40, v54
	v_div_scale_f32 v52, vcc, 1.0, v50, 1.0
	v_mul_f32_e32 v55, v52, v54
	v_fma_f32 v40, -v51, v55, v52
	v_mov_b32_e32 v42, v47
	v_fmac_f32_e32 v55, v40, v54
	v_pk_mul_f32 v[40:41], v[42:43], v[48:49] op_sel_hi:[1,0]
	v_fma_f32 v43, -v51, v55, v52
	v_mul_f32_e32 v42, 0xbfb8aa3b, v41
	v_exp_f32_e32 v42, v42
	v_div_fmas_f32 v43, v43, v54, v55
	v_add_f32_e32 v47, 1.0, v42
	v_div_scale_f32 v51, s[0:1], v47, v47, 1.0
	v_rcp_f32_e32 v52, v51
	v_div_fixup_f32 v42, v43, v50, 1.0
	v_mul_f32_e32 v42, v45, v42
	v_mul_f32_e32 v44, v44, v42
	v_fma_f32 v42, -v51, v52, 1.0
	v_fmac_f32_e32 v52, v42, v52
	v_div_scale_f32 v45, vcc, 1.0, v47, 1.0
	v_mul_f32_e32 v50, v45, v52
	v_fma_f32 v42, -v51, v50, v45
	v_fmac_f32_e32 v50, v42, v52
	v_mov_b32_e32 v42, v36
	v_mov_b32_e32 v43, v32
	v_pk_mul_f32 v[42:43], v[42:43], v[48:49] op_sel_hi:[1,0]
	v_fma_f32 v36, -v51, v50, v45
	v_mul_f32_e32 v32, 0xbfb8aa3b, v43
	v_exp_f32_e32 v32, v32
	v_div_fmas_f32 v36, v36, v52, v50
	v_add_f32_e32 v45, 1.0, v32
	v_div_scale_f32 v50, s[0:1], v45, v45, 1.0
	v_rcp_f32_e32 v51, v50
	v_div_fixup_f32 v32, v36, v47, 1.0
	v_mul_f32_e32 v32, v41, v32
	v_mul_f32_e32 v40, v40, v32
	v_fma_f32 v32, -v50, v51, 1.0
	v_fmac_f32_e32 v51, v32, v51
	v_div_scale_f32 v36, vcc, 1.0, v45, 1.0
	v_mul_f32_e32 v41, v36, v51
	v_fma_f32 v32, -v50, v41, v36
	v_fmac_f32_e32 v41, v32, v51
	v_mov_b32_e32 v32, v37
	v_pk_mul_f32 v[32:33], v[32:33], v[48:49] op_sel_hi:[1,0]
	v_fma_f32 v36, -v50, v41, v36
	v_mul_f32_e32 v37, 0xbfb8aa3b, v33
	v_exp_f32_e32 v37, v37
	v_div_fmas_f32 v36, v36, v51, v41
	v_div_fixup_f32 v36, v36, v45, 1.0
	v_mul_f32_e32 v36, v43, v36
	v_add_f32_e32 v41, 1.0, v37
	v_div_scale_f32 v47, s[0:1], v41, v41, 1.0
	v_rcp_f32_e32 v50, v47
	v_mul_f32_e32 v42, v42, v36
	v_div_scale_f32 v43, vcc, 1.0, v41, 1.0
	v_fma_f32 v36, -v47, v50, 1.0
	v_fmac_f32_e32 v50, v36, v50
	v_mul_f32_e32 v45, v43, v50
	v_fma_f32 v36, -v47, v45, v43
	v_fmac_f32_e32 v45, v36, v50
	v_mov_b32_e32 v36, v38
	v_mov_b32_e32 v37, v34
	v_pk_mul_f32 v[36:37], v[36:37], v[48:49] op_sel_hi:[1,0]
	v_fma_f32 v38, -v47, v45, v43
	v_mul_f32_e32 v34, 0xbfb8aa3b, v37
	v_exp_f32_e32 v34, v34
	v_div_fmas_f32 v38, v38, v50, v45
	v_add_f32_e32 v43, 1.0, v34
	v_div_scale_f32 v45, s[0:1], v43, v43, 1.0
	v_rcp_f32_e32 v47, v45
	v_div_fixup_f32 v34, v38, v41, 1.0
	v_mul_f32_e32 v33, v33, v34
	v_mul_f32_e32 v38, v32, v33
	v_fma_f32 v32, -v45, v47, 1.0
	v_fmac_f32_e32 v47, v32, v47
	v_div_scale_f32 v41, vcc, 1.0, v43, 1.0
	v_mul_f32_e32 v50, v41, v47
	v_fma_f32 v32, -v45, v50, v41
	v_mov_b32_e32 v34, v39
	v_fmac_f32_e32 v50, v32, v47
	v_pk_mul_f32 v[32:33], v[34:35], v[48:49] op_sel_hi:[1,0]
	v_fma_f32 v35, -v45, v50, v41
	v_mul_f32_e32 v34, 0xbfb8aa3b, v33
	v_exp_f32_e32 v34, v34
	v_div_fmas_f32 v35, v35, v47, v50
	v_div_fixup_f32 v35, v35, v43, 1.0
	v_mul_f32_e32 v35, v37, v35
	v_add_f32_e32 v34, 1.0, v34
	v_div_scale_f32 v39, s[0:1], v34, v34, 1.0
	v_rcp_f32_e32 v41, v39
	v_mul_f32_e32 v35, v36, v35
	v_fma_f32 v36, -v39, v41, 1.0
	v_fmac_f32_e32 v41, v36, v41
	v_div_scale_f32 v36, vcc, 1.0, v34, 1.0
	v_mul_f32_e32 v37, v36, v41
	v_fma_f32 v43, -v39, v37, v36
	v_fmac_f32_e32 v37, v43, v41
	v_fma_f32 v36, -v39, v37, v36
	v_div_fmas_f32 v36, v36, v41, v37
	v_div_fixup_f32 v34, v36, v34, 1.0
	v_mul_f32_e32 v33, v33, v34
	v_mul_f32_e32 v36, v32, v33
	v_cvt_pk_bf16_f32 v32, v49, v46
	v_cvt_pk_bf16_f32 v33, v44, v40
	v_cvt_pk_bf16_f32 v34, v42, v38
	v_cvt_pk_bf16_f32 v35, v35, v36
	v_mad_i64_i32 v[36:37], s[0:1], v53, s59, v[112:113]
	v_lshl_add_u64 v[36:37], v[36:37], 0, v[114:115]
	global_store_dwordx4 v[36:37], v[32:35], off
	s_nop 0
	v_add_u32_e32 v37, 0xa0, v142
	v_mov_b32_e32 v34, v28
	v_mov_b32_e32 v35, v24
	v_mov_b32_e32 v32, v238
	v_pk_mul_f32 v[34:35], v[34:35], v[32:33] op_sel_hi:[1,0]
	s_nop 0
	v_mul_f32_e32 v24, 0xbfb8aa3b, v35
	v_exp_f32_e32 v24, v24
	s_nop 0
	v_add_f32_e32 v28, 1.0, v24
	v_div_scale_f32 v33, s[0:1], v28, v28, 1.0
	v_rcp_f32_e32 v36, v33
	v_div_scale_f32 v38, vcc, 1.0, v28, 1.0
	v_fma_f32 v24, -v33, v36, 1.0
	v_fmac_f32_e32 v36, v24, v36
	v_mul_f32_e32 v39, v38, v36
	v_fma_f32 v24, -v33, v39, v38
	v_fmac_f32_e32 v39, v24, v36
	v_mov_b32_e32 v24, v29
	v_pk_mul_f32 v[24:25], v[24:25], v[32:33] op_sel_hi:[1,0]
	v_fma_f32 v33, -v33, v39, v38
	v_mul_f32_e32 v29, 0xbfb8aa3b, v25
	v_exp_f32_e32 v29, v29
	v_div_fmas_f32 v33, v33, v36, v39
	v_div_fixup_f32 v28, v33, v28, 1.0
	v_mul_f32_e32 v28, v35, v28
	v_add_f32_e32 v36, 1.0, v29
	v_div_scale_f32 v38, s[0:1], v36, v36, 1.0
	v_rcp_f32_e32 v39, v38
	v_mul_f32_e32 v33, v34, v28
	v_div_scale_f32 v34, vcc, 1.0, v36, 1.0
	v_fma_f32 v28, -v38, v39, 1.0
	v_fmac_f32_e32 v39, v28, v39
	v_mul_f32_e32 v35, v34, v39
	v_fma_f32 v28, -v38, v35, v34
	v_fmac_f32_e32 v35, v28, v39
	v_mov_b32_e32 v28, v30
	v_mov_b32_e32 v29, v26
	v_pk_mul_f32 v[28:29], v[28:29], v[32:33] op_sel_hi:[1,0]
	v_fma_f32 v30, -v38, v35, v34
	v_mul_f32_e32 v26, 0xbfb8aa3b, v29
	v_exp_f32_e32 v26, v26
	v_div_fmas_f32 v30, v30, v39, v35
	v_add_f32_e32 v34, 1.0, v26
	v_div_scale_f32 v35, s[0:1], v34, v34, 1.0
	v_rcp_f32_e32 v38, v35
	v_div_fixup_f32 v26, v30, v36, 1.0
	v_mul_f32_e32 v25, v25, v26
	v_mul_f32_e32 v30, v24, v25
	v_fma_f32 v24, -v35, v38, 1.0
	v_fmac_f32_e32 v38, v24, v38
	v_div_scale_f32 v36, vcc, 1.0, v34, 1.0
	v_mul_f32_e32 v39, v36, v38
	v_fma_f32 v24, -v35, v39, v36
	v_mov_b32_e32 v26, v31
	v_fmac_f32_e32 v39, v24, v38
	v_pk_mul_f32 v[24:25], v[26:27], v[32:33] op_sel_hi:[1,0]
	v_fma_f32 v27, -v35, v39, v36
	v_mul_f32_e32 v26, 0xbfb8aa3b, v25
	v_exp_f32_e32 v26, v26
	v_div_fmas_f32 v27, v27, v38, v39
	v_add_f32_e32 v31, 1.0, v26
	v_div_scale_f32 v35, s[0:1], v31, v31, 1.0
	v_rcp_f32_e32 v36, v35
	v_div_fixup_f32 v26, v27, v34, 1.0
	v_mul_f32_e32 v26, v29, v26
	v_mul_f32_e32 v28, v28, v26
	v_fma_f32 v26, -v35, v36, 1.0
	v_fmac_f32_e32 v36, v26, v36
	v_div_scale_f32 v29, vcc, 1.0, v31, 1.0
	v_mul_f32_e32 v34, v29, v36
	v_fma_f32 v26, -v35, v34, v29
	v_fmac_f32_e32 v34, v26, v36
	v_mov_b32_e32 v26, v20
	v_mov_b32_e32 v27, v16
	v_pk_mul_f32 v[26:27], v[26:27], v[32:33] op_sel_hi:[1,0]
	v_fma_f32 v20, -v35, v34, v29
	v_mul_f32_e32 v16, 0xbfb8aa3b, v27
	v_exp_f32_e32 v16, v16
	v_div_fmas_f32 v20, v20, v36, v34
	v_add_f32_e32 v29, 1.0, v16
	v_div_scale_f32 v34, s[0:1], v29, v29, 1.0
	v_rcp_f32_e32 v35, v34
	v_div_fixup_f32 v16, v20, v31, 1.0
	v_mul_f32_e32 v16, v25, v16
	v_mul_f32_e32 v24, v24, v16
	v_fma_f32 v16, -v34, v35, 1.0
	v_fmac_f32_e32 v35, v16, v35
	v_div_scale_f32 v20, vcc, 1.0, v29, 1.0
	v_mul_f32_e32 v25, v20, v35
	v_fma_f32 v16, -v34, v25, v20
	v_fmac_f32_e32 v25, v16, v35
	v_mov_b32_e32 v16, v21
	v_pk_mul_f32 v[16:17], v[16:17], v[32:33] op_sel_hi:[1,0]
	v_fma_f32 v20, -v34, v25, v20
	v_mul_f32_e32 v21, 0xbfb8aa3b, v17
	v_exp_f32_e32 v21, v21
	v_div_fmas_f32 v20, v20, v35, v25
	v_div_fixup_f32 v20, v20, v29, 1.0
	v_mul_f32_e32 v20, v27, v20
	v_add_f32_e32 v25, 1.0, v21
	v_div_scale_f32 v31, s[0:1], v25, v25, 1.0
	v_rcp_f32_e32 v34, v31
	v_mul_f32_e32 v26, v26, v20
	v_div_scale_f32 v27, vcc, 1.0, v25, 1.0
	v_fma_f32 v20, -v31, v34, 1.0
	v_fmac_f32_e32 v34, v20, v34
	v_mul_f32_e32 v29, v27, v34
	v_fma_f32 v20, -v31, v29, v27
	v_fmac_f32_e32 v29, v20, v34
	v_mov_b32_e32 v20, v22
	v_mov_b32_e32 v21, v18
	v_pk_mul_f32 v[20:21], v[20:21], v[32:33] op_sel_hi:[1,0]
	v_fma_f32 v22, -v31, v29, v27
	v_mul_f32_e32 v18, 0xbfb8aa3b, v21
	v_exp_f32_e32 v18, v18
	v_div_fmas_f32 v22, v22, v34, v29
	v_add_f32_e32 v27, 1.0, v18
	v_div_scale_f32 v29, s[0:1], v27, v27, 1.0
	v_rcp_f32_e32 v31, v29
	v_div_fixup_f32 v18, v22, v25, 1.0
	v_mul_f32_e32 v17, v17, v18
	v_mul_f32_e32 v22, v16, v17
	v_fma_f32 v16, -v29, v31, 1.0
	v_fmac_f32_e32 v31, v16, v31
	v_div_scale_f32 v25, vcc, 1.0, v27, 1.0
	v_mul_f32_e32 v34, v25, v31
	v_fma_f32 v16, -v29, v34, v25
	v_mov_b32_e32 v18, v23
	v_fmac_f32_e32 v34, v16, v31
	v_pk_mul_f32 v[16:17], v[18:19], v[32:33] op_sel_hi:[1,0]
	v_fma_f32 v19, -v29, v34, v25
	v_mul_f32_e32 v18, 0xbfb8aa3b, v17
	v_exp_f32_e32 v18, v18
	v_div_fmas_f32 v19, v19, v31, v34
	v_div_fixup_f32 v19, v19, v27, 1.0
	v_mul_f32_e32 v19, v21, v19
	v_add_f32_e32 v18, 1.0, v18
	v_div_scale_f32 v23, s[0:1], v18, v18, 1.0
	v_rcp_f32_e32 v25, v23
	v_mul_f32_e32 v19, v20, v19
	v_fma_f32 v20, -v23, v25, 1.0
	v_fmac_f32_e32 v25, v20, v25
	v_div_scale_f32 v20, vcc, 1.0, v18, 1.0
	v_mul_f32_e32 v21, v20, v25
	v_fma_f32 v27, -v23, v21, v20
	v_fmac_f32_e32 v21, v27, v25
	v_fma_f32 v20, -v23, v21, v20
	v_div_fmas_f32 v20, v20, v25, v21
	v_div_fixup_f32 v18, v20, v18, 1.0
	v_mul_f32_e32 v17, v17, v18
	v_mul_f32_e32 v20, v16, v17
	v_cvt_pk_bf16_f32 v16, v33, v30
	v_cvt_pk_bf16_f32 v17, v28, v24
	v_cvt_pk_bf16_f32 v18, v26, v22
	v_cvt_pk_bf16_f32 v19, v19, v20
	v_mad_i64_i32 v[20:21], s[0:1], v37, s59, v[112:113]
	v_lshl_add_u64 v[20:21], v[20:21], 0, v[114:115]
	global_store_dwordx4 v[20:21], v[16:19], off
	s_nop 0
	v_add_u32_e32 v21, 0xb0, v142
	v_mov_b32_e32 v18, v12
	v_mov_b32_e32 v19, v8
	v_mov_b32_e32 v16, v239
	v_pk_mul_f32 v[18:19], v[18:19], v[16:17] op_sel_hi:[1,0]
	s_nop 0
	v_mul_f32_e32 v8, 0xbfb8aa3b, v19
	v_exp_f32_e32 v8, v8
	s_nop 0
	v_add_f32_e32 v12, 1.0, v8
	v_div_scale_f32 v17, s[0:1], v12, v12, 1.0
	v_rcp_f32_e32 v20, v17
	v_div_scale_f32 v22, vcc, 1.0, v12, 1.0
	v_fma_f32 v8, -v17, v20, 1.0
	v_fmac_f32_e32 v20, v8, v20
	v_mul_f32_e32 v23, v22, v20
	v_fma_f32 v8, -v17, v23, v22
	v_fmac_f32_e32 v23, v8, v20
	v_mov_b32_e32 v8, v13
	v_pk_mul_f32 v[8:9], v[8:9], v[16:17] op_sel_hi:[1,0]
	v_fma_f32 v17, -v17, v23, v22
	v_mul_f32_e32 v13, 0xbfb8aa3b, v9
	v_exp_f32_e32 v13, v13
	v_div_fmas_f32 v17, v17, v20, v23
	v_div_fixup_f32 v12, v17, v12, 1.0
	v_mul_f32_e32 v12, v19, v12
	v_add_f32_e32 v20, 1.0, v13
	v_div_scale_f32 v22, s[0:1], v20, v20, 1.0
	v_rcp_f32_e32 v23, v22
	v_mul_f32_e32 v17, v18, v12
	v_div_scale_f32 v18, vcc, 1.0, v20, 1.0
	v_fma_f32 v12, -v22, v23, 1.0
	v_fmac_f32_e32 v23, v12, v23
	v_mul_f32_e32 v19, v18, v23
	v_fma_f32 v12, -v22, v19, v18
	v_fmac_f32_e32 v19, v12, v23
	v_mov_b32_e32 v12, v14
	v_mov_b32_e32 v13, v10
	v_pk_mul_f32 v[12:13], v[12:13], v[16:17] op_sel_hi:[1,0]
	v_fma_f32 v14, -v22, v19, v18
	v_mul_f32_e32 v10, 0xbfb8aa3b, v13
	v_exp_f32_e32 v10, v10
	v_div_fmas_f32 v14, v14, v23, v19
	v_add_f32_e32 v18, 1.0, v10
	v_div_scale_f32 v19, s[0:1], v18, v18, 1.0
	v_rcp_f32_e32 v22, v19
	v_div_fixup_f32 v10, v14, v20, 1.0
	v_mul_f32_e32 v9, v9, v10
	v_mul_f32_e32 v14, v8, v9
	v_fma_f32 v8, -v19, v22, 1.0
	v_fmac_f32_e32 v22, v8, v22
	v_div_scale_f32 v20, vcc, 1.0, v18, 1.0
	v_mul_f32_e32 v23, v20, v22
	v_fma_f32 v8, -v19, v23, v20
	v_mov_b32_e32 v10, v15
	v_fmac_f32_e32 v23, v8, v22
	v_pk_mul_f32 v[8:9], v[10:11], v[16:17] op_sel_hi:[1,0]
	v_fma_f32 v11, -v19, v23, v20
	v_mul_f32_e32 v10, 0xbfb8aa3b, v9
	v_exp_f32_e32 v10, v10
	v_div_fmas_f32 v11, v11, v22, v23
	v_add_f32_e32 v15, 1.0, v10
	v_div_scale_f32 v19, s[0:1], v15, v15, 1.0
	v_rcp_f32_e32 v20, v19
	v_div_fixup_f32 v10, v11, v18, 1.0
	v_mul_f32_e32 v10, v13, v10
	v_mul_f32_e32 v12, v12, v10
	v_fma_f32 v10, -v19, v20, 1.0
	v_fmac_f32_e32 v20, v10, v20
	v_div_scale_f32 v13, vcc, 1.0, v15, 1.0
	v_mul_f32_e32 v18, v13, v20
	v_fma_f32 v10, -v19, v18, v13
	v_fmac_f32_e32 v18, v10, v20
	v_mov_b32_e32 v10, v0
	v_mov_b32_e32 v11, v4
	v_pk_mul_f32 v[10:11], v[10:11], v[16:17] op_sel_hi:[1,0]
	v_fma_f32 v4, -v19, v18, v13
	v_mul_f32_e32 v0, 0xbfb8aa3b, v11
	v_exp_f32_e32 v0, v0
	v_div_fmas_f32 v4, v4, v20, v18
	v_add_f32_e32 v13, 1.0, v0
	v_div_scale_f32 v18, s[0:1], v13, v13, 1.0
	v_rcp_f32_e32 v19, v18
	v_div_fixup_f32 v0, v4, v15, 1.0
	v_mul_f32_e32 v0, v9, v0
	v_mul_f32_e32 v8, v8, v0
	v_fma_f32 v0, -v18, v19, 1.0
	v_fmac_f32_e32 v19, v0, v19
	v_div_scale_f32 v9, vcc, 1.0, v13, 1.0
	v_mul_f32_e32 v15, v9, v19
	v_fma_f32 v0, -v18, v15, v9
	v_mov_b32_e32 v4, v1
	v_fmac_f32_e32 v15, v0, v19
	v_pk_mul_f32 v[0:1], v[4:5], v[16:17] op_sel_hi:[1,0]
	v_fma_f32 v5, -v18, v15, v9
	v_mul_f32_e32 v4, 0xbfb8aa3b, v1
	v_exp_f32_e32 v4, v4
	v_div_fmas_f32 v5, v5, v19, v15
	v_add_f32_e32 v9, 1.0, v4
	v_div_scale_f32 v15, s[0:1], v9, v9, 1.0
	v_rcp_f32_e32 v18, v15
	v_div_fixup_f32 v4, v5, v13, 1.0
	v_mul_f32_e32 v4, v11, v4
	v_mul_f32_e32 v10, v10, v4
	v_fma_f32 v4, -v15, v18, 1.0
	v_fmac_f32_e32 v18, v4, v18
	v_div_scale_f32 v11, vcc, 1.0, v9, 1.0
	v_mul_f32_e32 v13, v11, v18
	v_fma_f32 v4, -v15, v13, v11
	v_fmac_f32_e32 v13, v4, v18
	v_mov_b32_e32 v4, v2
	v_mov_b32_e32 v5, v6
	v_pk_mul_f32 v[4:5], v[4:5], v[16:17] op_sel_hi:[1,0]
	v_fma_f32 v6, -v15, v13, v11
	v_mul_f32_e32 v2, 0xbfb8aa3b, v5
	v_exp_f32_e32 v2, v2
	v_div_fmas_f32 v6, v6, v18, v13
	v_div_fixup_f32 v6, v6, v9, 1.0
	v_mul_f32_e32 v1, v1, v6
	v_add_f32_e32 v2, 1.0, v2
	v_div_scale_f32 v11, s[0:1], v2, v2, 1.0
	v_rcp_f32_e32 v13, v11
	v_mul_f32_e32 v9, v0, v1
	v_div_scale_f32 v15, vcc, 1.0, v2, 1.0
	v_fma_f32 v0, -v11, v13, 1.0
	v_fmac_f32_e32 v13, v0, v13
	v_mul_f32_e32 v18, v15, v13
	v_fma_f32 v0, -v11, v18, v15
	v_mov_b32_e32 v6, v3
	v_fmac_f32_e32 v18, v0, v13
	v_pk_mul_f32 v[0:1], v[6:7], v[16:17] op_sel_hi:[1,0]
	v_fma_f32 v6, -v11, v18, v15
	v_mul_f32_e32 v3, 0xbfb8aa3b, v1
	v_exp_f32_e32 v3, v3
	v_div_fmas_f32 v6, v6, v13, v18
	v_div_fixup_f32 v2, v6, v2, 1.0
	v_mul_f32_e32 v2, v5, v2
	v_add_f32_e32 v3, 1.0, v3
	v_div_scale_f32 v7, s[0:1], v3, v3, 1.0
	v_rcp_f32_e32 v11, v7
	v_mul_f32_e32 v4, v4, v2
	v_fma_f32 v2, -v7, v11, 1.0
	v_fmac_f32_e32 v11, v2, v11
	v_div_scale_f32 v2, vcc, 1.0, v3, 1.0
	v_mul_f32_e32 v5, v2, v11
	v_fma_f32 v6, -v7, v5, v2
	v_fmac_f32_e32 v5, v6, v11
	v_fma_f32 v2, -v7, v5, v2
	v_div_fmas_f32 v2, v2, v11, v5
	v_div_fixup_f32 v2, v2, v3, 1.0
	v_mul_f32_e32 v1, v1, v2
	v_mul_f32_e32 v3, v0, v1
	v_cvt_pk_bf16_f32 v0, v17, v14
	v_cvt_pk_bf16_f32 v1, v12, v8
	v_cvt_pk_bf16_f32 v2, v10, v9
	v_cvt_pk_bf16_f32 v3, v4, v3
	v_mad_i64_i32 v[4:5], s[0:1], v21, s59, v[112:113]
	v_lshl_add_u64 v[4:5], v[4:5], 0, v[114:115]
	s_and_b64 vcc, exec, s[2:3]
	s_mov_b64 s[2:3], -1
	global_store_dwordx4 v[4:5], v[0:3], off
	s_cbranch_vccnz .LBB0_1486
	s_andn2_b64 vcc, exec, s[16:17]
	s_cbranch_vccnz .LBB0_1485
	s_barrier
	s_branch .LBB0_1485

; template <bool COOP>
; __global__ void __launch_bounds__(NTHR, 2) mega(Args args) {
	.amdhsa_kernel _Z4megaILb1EEv4Args
		.amdhsa_group_segment_fixed_size 0
		.amdhsa_private_segment_fixed_size 0
		.amdhsa_kernarg_size 480
		.amdhsa_user_sgpr_count 2
		.amdhsa_user_sgpr_dispatch_ptr 0
		.amdhsa_user_sgpr_queue_ptr 0
		.amdhsa_user_sgpr_kernarg_segment_ptr 1
		.amdhsa_user_sgpr_dispatch_id 0
		.amdhsa_user_sgpr_kernarg_preload_length 0
		.amdhsa_user_sgpr_kernarg_preload_offset 0
		.amdhsa_user_sgpr_private_segment_size 0
		.amdhsa_uses_dynamic_stack 0
		.amdhsa_enable_private_segment 0
		.amdhsa_system_sgpr_workgroup_id_x 1
		.amdhsa_system_sgpr_workgroup_id_y 0
		.amdhsa_system_sgpr_workgroup_id_z 0
		.amdhsa_system_sgpr_workgroup_info 0
		.amdhsa_system_vgpr_workitem_id 2
		.amdhsa_next_free_vgpr 256
		.amdhsa_next_free_sgpr 98
		.amdhsa_accum_offset 256
		.amdhsa_reserve_vcc 1
		.amdhsa_float_round_mode_32 0
		.amdhsa_float_round_mode_16_64 0
		.amdhsa_float_denorm_mode_32 3
		.amdhsa_float_denorm_mode_16_64 3
		.amdhsa_dx10_clamp 1
		.amdhsa_ieee_mode 1
		.amdhsa_fp16_overflow 0
		.amdhsa_tg_split 0
		.amdhsa_exception_fp_ieee_invalid_op 0
		.amdhsa_exception_fp_denorm_src 0
		.amdhsa_exception_fp_ieee_div_zero 0
		.amdhsa_exception_fp_ieee_overflow 0
		.amdhsa_exception_fp_ieee_underflow 0
		.amdhsa_exception_fp_ieee_inexact 0
		.amdhsa_exception_int_div_zero 0
	.end_amdhsa_kernel

; template <bool COOP>
; __global__ void __launch_bounds__(NTHR, 2) mega(Args args) {
amdhsa.kernels:
  - .agpr_count:     0
    .args:
      - .offset:         0
        .size:           224
        .value_kind:     by_value
      - .offset:         224
        .size:           4
        .value_kind:     hidden_block_count_x
      - .offset:         228
        .size:           4
        .value_kind:     hidden_block_count_y
      - .offset:         232
        .size:           4
        .value_kind:     hidden_block_count_z
      - .offset:         236
        .size:           2
        .value_kind:     hidden_group_size_x
      - .offset:         238
        .size:           2
        .value_kind:     hidden_group_size_y
      - .offset:         240
        .size:           2
        .value_kind:     hidden_group_size_z
      - .offset:         242
        .size:           2
        .value_kind:     hidden_remainder_x
      - .offset:         244
        .size:           2
        .value_kind:     hidden_remainder_y
      - .offset:         246
        .size:           2
        .value_kind:     hidden_remainder_z
      - .offset:         264
        .size:           8
        .value_kind:     hidden_global_offset_x
      - .offset:         272
        .size:           8
        .value_kind:     hidden_global_offset_y
      - .offset:         280
        .size:           8
        .value_kind:     hidden_global_offset_z
      - .offset:         288
        .size:           2
        .value_kind:     hidden_grid_dims
      - .offset:         312
        .size:           8
        .value_kind:     hidden_multigrid_sync_arg
      - .offset:         344
        .size:           4
        .value_kind:     hidden_dynamic_lds_size
    .group_segment_fixed_size: 0
    .kernarg_segment_align: 8
    .kernarg_segment_size: 480
    .language:       OpenCL C
    .language_version:
      - 2
      - 0
    .max_flat_workgroup_size: 512
    .name:           _Z4megaILb1EEv4Args
    .private_segment_fixed_size: 0
    .sgpr_count:     104
    .sgpr_spill_count: 9
    .symbol:         _Z4megaILb1EEv4Args.kd
    .uniform_work_group_size: 1
    .uses_dynamic_stack: false
    .vgpr_count:     256
    .vgpr_spill_count: 0
    .wavefront_size: 64
  - .agpr_count:     0
    .args:
      - .offset:         0
        .size:           224
        .value_kind:     by_value
      - .offset:         224
        .size:           4
        .value_kind:     hidden_block_count_x
      - .offset:         228
        .size:           4
        .value_kind:     hidden_block_count_y
      - .offset:         232
        .size:           4
        .value_kind:     hidden_block_count_z
      - .offset:         236
        .size:           2
        .value_kind:     hidden_group_size_x
      - .offset:         238
        .size:           2
        .value_kind:     hidden_group_size_y
      - .offset:         240
        .size:           2
        .value_kind:     hidden_group_size_z
      - .offset:         242
        .size:           2
        .value_kind:     hidden_remainder_x
      - .offset:         244
        .size:           2
        .value_kind:     hidden_remainder_y
      - .offset:         246
        .size:           2
        .value_kind:     hidden_remainder_z
      - .offset:         264
        .size:           8
        .value_kind:     hidden_global_offset_x
      - .offset:         272
        .size:           8
        .value_kind:     hidden_global_offset_y
      - .offset:         280
        .size:           8
        .value_kind:     hidden_global_offset_z
      - .offset:         288
        .size:           2
        .value_kind:     hidden_grid_dims
      - .offset:         344
        .size:           4
        .value_kind:     hidden_dynamic_lds_size
    .group_segment_fixed_size: 0
    .kernarg_segment_align: 8
    .kernarg_segment_size: 480
    .language:       OpenCL C
    .language_version:
      - 2
      - 0
    .max_flat_workgroup_size: 512
    .name:           _Z4megaILb0EEv4Args
    .private_segment_fixed_size: 0
    .sgpr_count:     106
    .sgpr_spill_count: 11
    .symbol:         _Z4megaILb0EEv4Args.kd
    .uniform_work_group_size: 1
    .uses_dynamic_stack: false
    .vgpr_count:     232
    .vgpr_spill_count: 0
    .wavefront_size: 64
